# placement pin: heads of the 20 GEMM K-loops and the attention KV loop aligned to 64 bytes
# baseline (speedup 1.0000x reference)
.Lfw_1_b_p:
	s_barrier
	s_setprio 1
	v_mfma_f32_16x16x32_bf16 v[50:53], v[192:195], v[160:163], 0
	v_mfma_f32_16x16x32_bf16 v[42:45], v[200:203], v[160:163], 0
	v_mfma_f32_16x16x32_bf16 v[34:37], v[192:195], v[168:171], 0
	v_mfma_f32_16x16x32_bf16 v[26:29], v[200:203], v[168:171], 0
	v_mfma_f32_16x16x32_bf16 v[18:21], v[192:195], v[176:179], 0
	v_mfma_f32_16x16x32_bf16 v[10:13], v[200:203], v[176:179], 0
	v_mfma_f32_16x16x32_bf16 v[6:9], v[192:195], v[184:187], 0
	v_mfma_f32_16x16x32_bf16 v[2:5], v[200:203], v[184:187], 0
	v_mfma_f32_16x16x32_bf16 v[50:53], v[196:199], v[164:167], v[50:53]
	v_mfma_f32_16x16x32_bf16 v[42:45], v[204:207], v[164:167], v[42:45]
	v_mfma_f32_16x16x32_bf16 v[34:37], v[196:199], v[172:175], v[34:37]
	v_mfma_f32_16x16x32_bf16 v[26:29], v[204:207], v[172:175], v[26:29]
	v_mfma_f32_16x16x32_bf16 v[18:21], v[196:199], v[180:183], v[18:21]
	v_mfma_f32_16x16x32_bf16 v[10:13], v[204:207], v[180:183], v[10:13]
	v_mfma_f32_16x16x32_bf16 v[6:9], v[196:199], v[188:191], v[6:9]
	v_mfma_f32_16x16x32_bf16 v[2:5], v[204:207], v[188:191], v[2:5]
	s_setprio 0
	s_barrier
	ds_read_b128 v[136:139], v150
	ds_read_b128 v[140:143], v150 offset:1024
	ds_read_b128 v[152:155], v150 offset:2048
	ds_read_b128 v[156:159], v150 offset:3072
	s_mov_b32 m0, s28
	s_add_i32 s33, s88, 0x40000
	ds_read_b128 v[160:163], v148 offset:32768
	ds_read_b128 v[164:167], v148 offset:33792
	ds_read_b128 v[168:171], v148 offset:34816
	ds_read_b128 v[172:175], v148 offset:35840
	ds_read_b128 v[176:179], v148 offset:36864
	ds_read_b128 v[180:183], v148 offset:37888
	ds_read_b128 v[184:187], v148 offset:38912
	ds_read_b128 v[188:191], v148 offset:39936
	buffer_load_dwordx4 v1, s[40:43], s33 offen lds
	s_add_i32 s33, s88, 0x60000
	s_mov_b32 m0, s29
	s_nop 0
	buffer_load_dwordx4 v1, s[40:43], s33 offen lds
	s_waitcnt lgkmcnt(8)
	s_barrier
	s_waitcnt lgkmcnt(0)
	s_setprio 1
	s_waitcnt lgkmcnt(7)
	v_mfma_f32_16x16x32_bf16 v[126:129], v[136:139], v[160:163], v[126:129]
	v_mfma_f32_16x16x32_bf16 v[122:125], v[152:155], v[160:163], v[122:125]
	s_waitcnt lgkmcnt(5)
	v_mfma_f32_16x16x32_bf16 v[118:121], v[136:139], v[168:171], v[118:121]
	v_mfma_f32_16x16x32_bf16 v[110:113], v[152:155], v[168:171], v[110:113]
	s_waitcnt lgkmcnt(3)
	v_mfma_f32_16x16x32_bf16 v[102:105], v[136:139], v[176:179], v[102:105]
	v_mfma_f32_16x16x32_bf16 v[94:97], v[152:155], v[176:179], v[94:97]
	s_waitcnt lgkmcnt(1)
	v_mfma_f32_16x16x32_bf16 v[86:89], v[136:139], v[184:187], v[86:89]
	v_mfma_f32_16x16x32_bf16 v[78:81], v[152:155], v[184:187], v[78:81]
	v_mfma_f32_16x16x32_bf16 v[126:129], v[140:143], v[164:167], v[126:129]
	v_mfma_f32_16x16x32_bf16 v[122:125], v[156:159], v[164:167], v[122:125]
	v_mfma_f32_16x16x32_bf16 v[118:121], v[140:143], v[172:175], v[118:121]
	v_mfma_f32_16x16x32_bf16 v[110:113], v[156:159], v[172:175], v[110:113]
	v_mfma_f32_16x16x32_bf16 v[102:105], v[140:143], v[180:183], v[102:105]
	v_mfma_f32_16x16x32_bf16 v[94:97], v[156:159], v[180:183], v[94:97]
	s_waitcnt lgkmcnt(0)
	v_mfma_f32_16x16x32_bf16 v[86:89], v[140:143], v[188:191], v[86:89]
	v_mfma_f32_16x16x32_bf16 v[78:81], v[156:159], v[188:191], v[78:81]
	s_setprio 0
	s_barrier
	s_mov_b32 m0, s31
	s_or_b32 s33, s87, 0x80
	ds_read_b128 v[192:195], v151
	ds_read_b128 v[196:199], v151 offset:1024
	ds_read_b128 v[200:203], v151 offset:2048
	ds_read_b128 v[204:207], v151 offset:3072
	buffer_load_dwordx4 v144, s[8:11], s33 offen lds
	s_add_i32 s33, s87, 0x20080
	s_mov_b32 m0, s34
	s_nop 0
	buffer_load_dwordx4 v144, s[8:11], s33 offen lds
	s_waitcnt vmcnt(10)
	s_barrier
	s_waitcnt lgkmcnt(0)
	s_setprio 1
	s_waitcnt lgkmcnt(3)
	v_mfma_f32_16x16x32_bf16 v[114:117], v[192:195], v[160:163], v[114:117]
	s_waitcnt lgkmcnt(1)
	v_mfma_f32_16x16x32_bf16 v[106:109], v[200:203], v[160:163], v[106:109]
	v_mfma_f32_16x16x32_bf16 v[98:101], v[192:195], v[168:171], v[98:101]
	v_mfma_f32_16x16x32_bf16 v[90:93], v[200:203], v[168:171], v[90:93]
	v_mfma_f32_16x16x32_bf16 v[82:85], v[192:195], v[176:179], v[82:85]
	v_mfma_f32_16x16x32_bf16 v[74:77], v[200:203], v[176:179], v[74:77]
	v_mfma_f32_16x16x32_bf16 v[70:73], v[192:195], v[184:187], v[70:73]
	v_mfma_f32_16x16x32_bf16 v[66:69], v[200:203], v[184:187], v[66:69]
	v_mfma_f32_16x16x32_bf16 v[114:117], v[196:199], v[164:167], v[114:117]
	s_waitcnt lgkmcnt(0)
	v_mfma_f32_16x16x32_bf16 v[106:109], v[204:207], v[164:167], v[106:109]
	v_mfma_f32_16x16x32_bf16 v[98:101], v[196:199], v[172:175], v[98:101]
	v_mfma_f32_16x16x32_bf16 v[90:93], v[204:207], v[172:175], v[90:93]
	v_mfma_f32_16x16x32_bf16 v[82:85], v[196:199], v[180:183], v[82:85]
	v_mfma_f32_16x16x32_bf16 v[74:77], v[204:207], v[180:183], v[74:77]
	v_mfma_f32_16x16x32_bf16 v[70:73], v[196:199], v[188:191], v[70:73]
	v_mfma_f32_16x16x32_bf16 v[66:69], v[204:207], v[188:191], v[66:69]
	s_setprio 0
	s_mov_b32 m0, s35
	s_barrier
	ds_read_b128 v[160:163], v148 offset:49152
	ds_read_b128 v[164:167], v148 offset:50176
	ds_read_b128 v[168:171], v148 offset:51200
	ds_read_b128 v[172:175], v148 offset:52224
	ds_read_b128 v[176:179], v148 offset:53248
	ds_read_b128 v[180:183], v148 offset:54272
	ds_read_b128 v[184:187], v148 offset:55296
	ds_read_b128 v[188:191], v148 offset:56320
	buffer_load_dwordx4 v1, s[40:43], s89 offen lds
	s_add_i32 s88, s88, 0x20080
	s_mov_b32 m0, s36
	s_nop 0
	buffer_load_dwordx4 v1, s[40:43], s88 offen lds
	s_barrier
	s_waitcnt lgkmcnt(0)
	s_setprio 1
	s_waitcnt lgkmcnt(7)
	v_mfma_f32_16x16x32_bf16 v[62:65], v[136:139], v[160:163], v[62:65]
	v_mfma_f32_16x16x32_bf16 v[58:61], v[152:155], v[160:163], v[58:61]
	s_waitcnt lgkmcnt(5)
	v_mfma_f32_16x16x32_bf16 v[54:57], v[136:139], v[168:171], v[54:57]
	v_mfma_f32_16x16x32_bf16 v[46:49], v[152:155], v[168:171], v[46:49]
	s_waitcnt lgkmcnt(3)
	v_mfma_f32_16x16x32_bf16 v[38:41], v[136:139], v[176:179], v[38:41]
	v_mfma_f32_16x16x32_bf16 v[30:33], v[152:155], v[176:179], v[30:33]
	s_waitcnt lgkmcnt(1)
	v_mfma_f32_16x16x32_bf16 v[22:25], v[136:139], v[184:187], v[22:25]
	v_mfma_f32_16x16x32_bf16 v[14:17], v[152:155], v[184:187], v[14:17]
	v_mfma_f32_16x16x32_bf16 v[62:65], v[140:143], v[164:167], v[62:65]
	v_mfma_f32_16x16x32_bf16 v[58:61], v[156:159], v[164:167], v[58:61]
	v_mfma_f32_16x16x32_bf16 v[54:57], v[140:143], v[172:175], v[54:57]
	v_mfma_f32_16x16x32_bf16 v[46:49], v[156:159], v[172:175], v[46:49]
	v_mfma_f32_16x16x32_bf16 v[38:41], v[140:143], v[180:183], v[38:41]
	v_mfma_f32_16x16x32_bf16 v[30:33], v[156:159], v[180:183], v[30:33]
	s_waitcnt lgkmcnt(0)
	v_mfma_f32_16x16x32_bf16 v[22:25], v[140:143], v[188:191], v[22:25]
	v_mfma_f32_16x16x32_bf16 v[14:17], v[156:159], v[188:191], v[14:17]
	s_setprio 0
	s_barrier
	s_mov_b32 m0, s37
	s_add_i32 s33, s87, 0x40080
	buffer_load_dwordx4 v144, s[8:11], s33 offen lds
	s_add_i32 s87, s87, 0x60080
	s_mov_b32 m0, s38
	s_nop 0
	buffer_load_dwordx4 v144, s[8:11], s87 offen lds
	s_waitcnt vmcnt(6)
	s_barrier
	s_setprio 1
	v_mfma_f32_16x16x32_bf16 v[50:53], v[192:195], v[160:163], v[50:53]
	v_mfma_f32_16x16x32_bf16 v[42:45], v[200:203], v[160:163], v[42:45]
	v_mfma_f32_16x16x32_bf16 v[34:37], v[192:195], v[168:171], v[34:37]
	v_mfma_f32_16x16x32_bf16 v[26:29], v[200:203], v[168:171], v[26:29]
	v_mfma_f32_16x16x32_bf16 v[18:21], v[192:195], v[176:179], v[18:21]
	v_mfma_f32_16x16x32_bf16 v[10:13], v[200:203], v[176:179], v[10:13]
	v_mfma_f32_16x16x32_bf16 v[6:9], v[192:195], v[184:187], v[6:9]
	v_mfma_f32_16x16x32_bf16 v[2:5], v[200:203], v[184:187], v[2:5]
	v_mfma_f32_16x16x32_bf16 v[50:53], v[196:199], v[164:167], v[50:53]
	v_mfma_f32_16x16x32_bf16 v[42:45], v[204:207], v[164:167], v[42:45]
	v_mfma_f32_16x16x32_bf16 v[34:37], v[196:199], v[172:175], v[34:37]
	v_mfma_f32_16x16x32_bf16 v[26:29], v[204:207], v[172:175], v[26:29]
	v_mfma_f32_16x16x32_bf16 v[18:21], v[196:199], v[180:183], v[18:21]
	v_mfma_f32_16x16x32_bf16 v[10:13], v[204:207], v[180:183], v[10:13]
	v_mfma_f32_16x16x32_bf16 v[6:9], v[196:199], v[188:191], v[6:9]
	v_mfma_f32_16x16x32_bf16 v[2:5], v[204:207], v[188:191], v[2:5]
	s_setprio 0
	s_add_i32 s86, s86, 2
	s_addk_i32 s7, 0x100
	s_addk_i32 s79, 0x100
	s_cmp_gt_u32 s86, 13
	s_barrier
	.p2align 6

.Lfw_2_b_p:
	s_barrier
	s_setprio 1
	v_mfma_f32_16x16x32_bf16 v[54:57], v[178:181], v[146:149], 0
	v_mfma_f32_16x16x32_bf16 v[46:49], v[190:193], v[146:149], 0
	v_mfma_f32_16x16x32_bf16 v[38:41], v[178:181], v[154:157], 0
	v_mfma_f32_16x16x32_bf16 v[30:33], v[190:193], v[154:157], 0
	v_mfma_f32_16x16x32_bf16 v[22:25], v[178:181], v[162:165], 0
	v_mfma_f32_16x16x32_bf16 v[14:17], v[190:193], v[162:165], 0
	v_mfma_f32_16x16x32_bf16 v[6:9], v[178:181], v[170:173], 0
	v_mfma_f32_16x16x32_bf16 v[2:5], v[190:193], v[170:173], 0
	v_mfma_f32_16x16x32_bf16 v[54:57], v[182:185], v[150:153], v[54:57]
	v_mfma_f32_16x16x32_bf16 v[46:49], v[202:205], v[150:153], v[46:49]
	v_mfma_f32_16x16x32_bf16 v[38:41], v[182:185], v[158:161], v[38:41]
	v_mfma_f32_16x16x32_bf16 v[30:33], v[202:205], v[158:161], v[30:33]
	v_mfma_f32_16x16x32_bf16 v[22:25], v[182:185], v[166:169], v[22:25]
	v_mfma_f32_16x16x32_bf16 v[14:17], v[202:205], v[166:169], v[14:17]
	v_mfma_f32_16x16x32_bf16 v[6:9], v[182:185], v[174:177], v[6:9]
	v_mfma_f32_16x16x32_bf16 v[2:5], v[202:205], v[174:177], v[2:5]
	s_setprio 0
	s_barrier
	ds_read_b128 v[118:121], v200
	ds_read_b128 v[126:129], v200 offset:1024
	ds_read_b128 v[130:133], v200 offset:2048
	ds_read_b128 v[138:141], v200 offset:3072
	s_mov_b32 m0, s26
	s_add_i32 s33, s87, 0x40000
	ds_read_b128 v[146:149], v198 offset:32768
	ds_read_b128 v[150:153], v198 offset:33792
	ds_read_b128 v[154:157], v198 offset:34816
	ds_read_b128 v[158:161], v198 offset:35840
	ds_read_b128 v[162:165], v198 offset:36864
	ds_read_b128 v[166:169], v198 offset:37888
	ds_read_b128 v[170:173], v198 offset:38912
	ds_read_b128 v[174:177], v198 offset:39936
	buffer_load_dwordx4 v1, s[48:51], s33 offen lds
	s_add_i32 s33, s87, 0x60000
	s_mov_b32 m0, s27
	s_nop 0
	buffer_load_dwordx4 v1, s[48:51], s33 offen lds
	s_waitcnt lgkmcnt(8)
	s_barrier
	s_waitcnt lgkmcnt(0)
	s_setprio 1
	s_waitcnt lgkmcnt(7)
	v_mfma_f32_16x16x32_bf16 v[142:145], v[118:121], v[146:149], v[142:145]
	v_mfma_f32_16x16x32_bf16 v[134:137], v[130:133], v[146:149], v[134:137]
	s_waitcnt lgkmcnt(5)
	v_mfma_f32_16x16x32_bf16 v[122:125], v[118:121], v[154:157], v[122:125]
	v_mfma_f32_16x16x32_bf16 v[114:117], v[130:133], v[154:157], v[114:117]
	s_waitcnt lgkmcnt(3)
	v_mfma_f32_16x16x32_bf16 v[94:97], v[118:121], v[162:165], v[94:97]
	v_mfma_f32_16x16x32_bf16 v[90:93], v[130:133], v[162:165], v[90:93]
	s_waitcnt lgkmcnt(1)
	v_mfma_f32_16x16x32_bf16 v[82:85], v[118:121], v[170:173], v[82:85]
	v_mfma_f32_16x16x32_bf16 v[74:77], v[130:133], v[170:173], v[74:77]
	v_mfma_f32_16x16x32_bf16 v[142:145], v[126:129], v[150:153], v[142:145]
	v_mfma_f32_16x16x32_bf16 v[134:137], v[138:141], v[150:153], v[134:137]
	v_mfma_f32_16x16x32_bf16 v[122:125], v[126:129], v[158:161], v[122:125]
	v_mfma_f32_16x16x32_bf16 v[114:117], v[138:141], v[158:161], v[114:117]
	v_mfma_f32_16x16x32_bf16 v[94:97], v[126:129], v[166:169], v[94:97]
	v_mfma_f32_16x16x32_bf16 v[90:93], v[138:141], v[166:169], v[90:93]
	s_waitcnt lgkmcnt(0)
	v_mfma_f32_16x16x32_bf16 v[82:85], v[126:129], v[174:177], v[82:85]
	v_mfma_f32_16x16x32_bf16 v[74:77], v[138:141], v[174:177], v[74:77]
	s_setprio 0
	s_barrier
	s_mov_b32 m0, s34
	s_add_i32 s33, s86, 0x80
	ds_read_b128 v[178:181], v201
	ds_read_b128 v[182:185], v201 offset:1024
	ds_read_b128 v[190:193], v201 offset:2048
	ds_read_b128 v[202:205], v201 offset:3072
	buffer_load_dwordx4 v194, s[8:11], s33 offen lds
	s_add_i32 s33, s86, 0x20080
	s_mov_b32 m0, s35
	s_nop 0
	buffer_load_dwordx4 v194, s[8:11], s33 offen lds
	s_waitcnt vmcnt(10)
	s_barrier
	s_waitcnt lgkmcnt(0)
	s_setprio 1
	s_waitcnt lgkmcnt(3)
	v_mfma_f32_16x16x32_bf16 v[110:113], v[178:181], v[146:149], v[110:113]
	s_waitcnt lgkmcnt(1)
	v_mfma_f32_16x16x32_bf16 v[106:109], v[190:193], v[146:149], v[106:109]
	v_mfma_f32_16x16x32_bf16 v[102:105], v[178:181], v[154:157], v[102:105]
	v_mfma_f32_16x16x32_bf16 v[98:101], v[190:193], v[154:157], v[98:101]
	v_mfma_f32_16x16x32_bf16 v[86:89], v[178:181], v[162:165], v[86:89]
	v_mfma_f32_16x16x32_bf16 v[78:81], v[190:193], v[162:165], v[78:81]
	v_mfma_f32_16x16x32_bf16 v[70:73], v[178:181], v[170:173], v[70:73]
	v_mfma_f32_16x16x32_bf16 v[66:69], v[190:193], v[170:173], v[66:69]
	v_mfma_f32_16x16x32_bf16 v[110:113], v[182:185], v[150:153], v[110:113]
	s_waitcnt lgkmcnt(0)
	v_mfma_f32_16x16x32_bf16 v[106:109], v[202:205], v[150:153], v[106:109]
	v_mfma_f32_16x16x32_bf16 v[102:105], v[182:185], v[158:161], v[102:105]
	v_mfma_f32_16x16x32_bf16 v[98:101], v[202:205], v[158:161], v[98:101]
	v_mfma_f32_16x16x32_bf16 v[86:89], v[182:185], v[166:169], v[86:89]
	v_mfma_f32_16x16x32_bf16 v[78:81], v[202:205], v[166:169], v[78:81]
	v_mfma_f32_16x16x32_bf16 v[70:73], v[182:185], v[174:177], v[70:73]
	v_mfma_f32_16x16x32_bf16 v[66:69], v[202:205], v[174:177], v[66:69]
	s_setprio 0
	s_mov_b32 m0, s36
	s_barrier
	ds_read_b128 v[146:149], v198 offset:49152
	ds_read_b128 v[150:153], v198 offset:50176
	ds_read_b128 v[154:157], v198 offset:51200
	ds_read_b128 v[158:161], v198 offset:52224
	ds_read_b128 v[162:165], v198 offset:53248
	ds_read_b128 v[166:169], v198 offset:54272
	ds_read_b128 v[170:173], v198 offset:55296
	ds_read_b128 v[174:177], v198 offset:56320
	buffer_load_dwordx4 v1, s[48:51], s88 offen lds
	s_add_i32 s87, s87, 0x20080
	s_mov_b32 m0, s37
	s_nop 0
	buffer_load_dwordx4 v1, s[48:51], s87 offen lds
	s_barrier
	s_waitcnt lgkmcnt(0)
	s_setprio 1
	s_waitcnt lgkmcnt(7)
	v_mfma_f32_16x16x32_bf16 v[62:65], v[118:121], v[146:149], v[62:65]
	v_mfma_f32_16x16x32_bf16 v[58:61], v[130:133], v[146:149], v[58:61]
	s_waitcnt lgkmcnt(5)
	v_mfma_f32_16x16x32_bf16 v[50:53], v[118:121], v[154:157], v[50:53]
	v_mfma_f32_16x16x32_bf16 v[42:45], v[130:133], v[154:157], v[42:45]
	s_waitcnt lgkmcnt(3)
	v_mfma_f32_16x16x32_bf16 v[34:37], v[118:121], v[162:165], v[34:37]
	v_mfma_f32_16x16x32_bf16 v[26:29], v[130:133], v[162:165], v[26:29]
	s_waitcnt lgkmcnt(1)
	v_mfma_f32_16x16x32_bf16 v[18:21], v[118:121], v[170:173], v[18:21]
	v_mfma_f32_16x16x32_bf16 v[10:13], v[130:133], v[170:173], v[10:13]
	v_mfma_f32_16x16x32_bf16 v[62:65], v[126:129], v[150:153], v[62:65]
	v_mfma_f32_16x16x32_bf16 v[58:61], v[138:141], v[150:153], v[58:61]
	v_mfma_f32_16x16x32_bf16 v[50:53], v[126:129], v[158:161], v[50:53]
	v_mfma_f32_16x16x32_bf16 v[42:45], v[138:141], v[158:161], v[42:45]
	v_mfma_f32_16x16x32_bf16 v[34:37], v[126:129], v[166:169], v[34:37]
	v_mfma_f32_16x16x32_bf16 v[26:29], v[138:141], v[166:169], v[26:29]
	s_waitcnt lgkmcnt(0)
	v_mfma_f32_16x16x32_bf16 v[18:21], v[126:129], v[174:177], v[18:21]
	v_mfma_f32_16x16x32_bf16 v[10:13], v[138:141], v[174:177], v[10:13]
	s_setprio 0
	s_barrier
	s_mov_b32 m0, s38
	s_add_i32 s33, s86, 0x40080
	buffer_load_dwordx4 v194, s[8:11], s33 offen lds
	s_add_i32 s86, s86, 0x60080
	s_mov_b32 m0, s39
	s_nop 0
	buffer_load_dwordx4 v194, s[8:11], s86 offen lds
	s_waitcnt vmcnt(6)
	s_barrier
	s_setprio 1
	v_mfma_f32_16x16x32_bf16 v[54:57], v[178:181], v[146:149], v[54:57]
	v_mfma_f32_16x16x32_bf16 v[46:49], v[190:193], v[146:149], v[46:49]
	v_mfma_f32_16x16x32_bf16 v[38:41], v[178:181], v[154:157], v[38:41]
	v_mfma_f32_16x16x32_bf16 v[30:33], v[190:193], v[154:157], v[30:33]
	v_mfma_f32_16x16x32_bf16 v[22:25], v[178:181], v[162:165], v[22:25]
	v_mfma_f32_16x16x32_bf16 v[14:17], v[190:193], v[162:165], v[14:17]
	v_mfma_f32_16x16x32_bf16 v[6:9], v[178:181], v[170:173], v[6:9]
	v_mfma_f32_16x16x32_bf16 v[2:5], v[190:193], v[170:173], v[2:5]
	v_mfma_f32_16x16x32_bf16 v[54:57], v[182:185], v[150:153], v[54:57]
	v_mfma_f32_16x16x32_bf16 v[46:49], v[202:205], v[150:153], v[46:49]
	v_mfma_f32_16x16x32_bf16 v[38:41], v[182:185], v[158:161], v[38:41]
	v_mfma_f32_16x16x32_bf16 v[30:33], v[202:205], v[158:161], v[30:33]
	v_mfma_f32_16x16x32_bf16 v[22:25], v[182:185], v[166:169], v[22:25]
	v_mfma_f32_16x16x32_bf16 v[14:17], v[202:205], v[166:169], v[14:17]
	v_mfma_f32_16x16x32_bf16 v[6:9], v[182:185], v[174:177], v[6:9]
	v_mfma_f32_16x16x32_bf16 v[2:5], v[202:205], v[174:177], v[2:5]
	s_setprio 0
	s_add_i32 s17, s17, 2
	s_addk_i32 s7, 0x100
	s_addk_i32 s16, 0x100
	s_cmp_gt_u32 s17, 13
	s_barrier
	.p2align 6

.LBB0_773:
	v_bfe_u32 v2, v193, 16, 16
	v_lshl_add_u32 v194, v2, 10, v1
	v_bfe_u32 v2, v192, 16, 16
	v_mov_b32_e32 v50, 0
	v_lshl_add_u32 v195, v2, 10, v1
	s_mov_b32 s8, -2
	s_movk_i32 s9, 0x100
	s_branch .LBB0_775_pr0
	.p2align 6

.Lfw_3_b:
	s_barrier
	s_setprio 1
	v_mfma_f32_16x16x128_f8f6f4 v[106:109], v[198:205], v[18:25], v[106:109]
	v_mfma_f32_16x16x128_f8f6f4 v[98:101], v[206:213], v[18:25], v[98:101]
	v_mfma_f32_16x16x128_f8f6f4 v[90:93], v[198:205], v[26:33], v[90:93]
	v_mfma_f32_16x16x128_f8f6f4 v[82:85], v[206:213], v[26:33], v[82:85]
	v_mfma_f32_16x16x128_f8f6f4 v[74:77], v[198:205], v[34:41], v[74:77]
	v_mfma_f32_16x16x128_f8f6f4 v[66:69], v[206:213], v[34:41], v[66:69]
	v_mfma_f32_16x16x128_f8f6f4 v[58:61], v[198:205], v[42:49], v[58:61]
	v_mfma_f32_16x16x128_f8f6f4 v[50:53], v[206:213], v[42:49], v[50:53]
	s_setprio 0
	v_add_u32_e32 v14, 0x18000, v189
	s_barrier
	ds_read_b128 v[2:5], v14
	ds_read_b128 v[6:9], v14 offset:1024
	ds_read_b128 v[10:13], v14 offset:2048
	ds_read_b128 v[14:17], v14 offset:3072
	s_mov_b32 m0, s23
	ds_read_b128 v[18:21], v191 offset:32768
	ds_read_b128 v[22:25], v191 offset:33792
	ds_read_b128 v[26:29], v191 offset:34816
	ds_read_b128 v[30:33], v191 offset:35840
	ds_read_b128 v[34:37], v191 offset:36864
	ds_read_b128 v[38:41], v191 offset:37888
	ds_read_b128 v[42:45], v191 offset:38912
	ds_read_b128 v[46:49], v191 offset:39936
	buffer_load_dwordx4 v196, s[40:43], s57 offen lds
	s_mov_b32 m0, s24
	s_nop 0
	buffer_load_dwordx4 v197, s[40:43], s57 offen lds
	s_waitcnt lgkmcnt(8)
	s_barrier
	s_waitcnt lgkmcnt(0)
	s_setprio 1
	s_waitcnt lgkmcnt(6)
	v_mfma_f32_16x16x128_f8f6f4 v[174:177], v[2:9], v[18:25], v[174:177]
	v_mfma_f32_16x16x128_f8f6f4 v[166:169], v[10:17], v[18:25], v[166:169]
	s_waitcnt lgkmcnt(4)
	v_mfma_f32_16x16x128_f8f6f4 v[158:161], v[2:9], v[26:33], v[158:161]
	v_mfma_f32_16x16x128_f8f6f4 v[150:153], v[10:17], v[26:33], v[150:153]
	s_waitcnt lgkmcnt(2)
	v_mfma_f32_16x16x128_f8f6f4 v[142:145], v[2:9], v[34:41], v[142:145]
	v_mfma_f32_16x16x128_f8f6f4 v[134:137], v[10:17], v[34:41], v[134:137]
	s_waitcnt lgkmcnt(0)
	v_mfma_f32_16x16x128_f8f6f4 v[126:129], v[2:9], v[42:49], v[126:129]
	v_mfma_f32_16x16x128_f8f6f4 v[118:121], v[10:17], v[42:49], v[118:121]
	s_setprio 0
	s_barrier
	s_mov_b32 m0, s26
	v_add_u32_e32 v208, 0x1c000, v189
	ds_read_b128 v[196:199], v208
	ds_read_b128 v[200:203], v208 offset:1024
	ds_read_b128 v[204:207], v208 offset:2048
	ds_read_b128 v[208:211], v208 offset:3072
	buffer_load_dwordx4 v184, s[12:15], s7 offen lds
	s_add_i32 s7, s6, 0x10080
	s_mov_b32 m0, s27
	s_nop 0
	buffer_load_dwordx4 v184, s[12:15], s7 offen lds
	s_waitcnt vmcnt(10)
	s_barrier
	s_waitcnt lgkmcnt(0)
	s_setprio 1
	s_waitcnt lgkmcnt(2)
	v_mfma_f32_16x16x128_f8f6f4 v[170:173], v[196:203], v[18:25], v[170:173]
	s_waitcnt lgkmcnt(0)
	v_mfma_f32_16x16x128_f8f6f4 v[162:165], v[204:211], v[18:25], v[162:165]
	v_mfma_f32_16x16x128_f8f6f4 v[154:157], v[196:203], v[26:33], v[154:157]
	v_mfma_f32_16x16x128_f8f6f4 v[146:149], v[204:211], v[26:33], v[146:149]
	v_mfma_f32_16x16x128_f8f6f4 v[138:141], v[196:203], v[34:41], v[138:141]
	v_mfma_f32_16x16x128_f8f6f4 v[130:133], v[204:211], v[34:41], v[130:133]
	v_mfma_f32_16x16x128_f8f6f4 v[122:125], v[196:203], v[42:49], v[122:125]
	v_mfma_f32_16x16x128_f8f6f4 v[114:117], v[204:211], v[42:49], v[114:117]
	s_setprio 0
	s_mov_b32 m0, s28
	s_barrier
	ds_read_b128 v[18:21], v191 offset:49152
	ds_read_b128 v[22:25], v191 offset:50176
	ds_read_b128 v[26:29], v191 offset:51200
	ds_read_b128 v[30:33], v191 offset:52224
	ds_read_b128 v[34:37], v191 offset:53248
	ds_read_b128 v[38:41], v191 offset:54272
	ds_read_b128 v[42:45], v191 offset:55296
	ds_read_b128 v[46:49], v191 offset:56320
	buffer_load_dwordx4 v214, s[40:43], s51 offen lds
	s_mov_b32 m0, s29
	s_nop 0
	buffer_load_dwordx4 v215, s[40:43], s51 offen lds
	s_barrier
	s_waitcnt lgkmcnt(0)
	s_setprio 1
	s_waitcnt lgkmcnt(6)
	v_mfma_f32_16x16x128_f8f6f4 v[110:113], v[2:9], v[18:25], v[110:113]
	v_mfma_f32_16x16x128_f8f6f4 v[102:105], v[10:17], v[18:25], v[102:105]
	s_waitcnt lgkmcnt(4)
	v_mfma_f32_16x16x128_f8f6f4 v[94:97], v[2:9], v[26:33], v[94:97]
	v_mfma_f32_16x16x128_f8f6f4 v[86:89], v[10:17], v[26:33], v[86:89]
	s_waitcnt lgkmcnt(2)
	v_mfma_f32_16x16x128_f8f6f4 v[78:81], v[2:9], v[34:41], v[78:81]
	v_mfma_f32_16x16x128_f8f6f4 v[70:73], v[10:17], v[34:41], v[70:73]
	s_waitcnt lgkmcnt(0)
	v_mfma_f32_16x16x128_f8f6f4 v[62:65], v[2:9], v[42:49], v[62:65]
	v_mfma_f32_16x16x128_f8f6f4 v[54:57], v[10:17], v[42:49], v[54:57]
	s_setprio 0
	s_barrier
	s_mov_b32 m0, s30
	s_add_i32 s7, s6, 0x20080
	buffer_load_dwordx4 v184, s[12:15], s7 offen lds
	s_add_i32 s6, s6, 0x30080
	s_mov_b32 m0, s31
	s_nop 0
	buffer_load_dwordx4 v184, s[12:15], s6 offen lds
	s_waitcnt vmcnt(6)
	s_barrier
	s_setprio 1
	v_mfma_f32_16x16x128_f8f6f4 v[106:109], v[196:203], v[18:25], v[106:109]
	v_mfma_f32_16x16x128_f8f6f4 v[98:101], v[204:211], v[18:25], v[98:101]
	v_mfma_f32_16x16x128_f8f6f4 v[90:93], v[196:203], v[26:33], v[90:93]
	v_mfma_f32_16x16x128_f8f6f4 v[82:85], v[204:211], v[26:33], v[82:85]
	v_mfma_f32_16x16x128_f8f6f4 v[74:77], v[196:203], v[34:41], v[74:77]
	v_mfma_f32_16x16x128_f8f6f4 v[66:69], v[204:211], v[34:41], v[66:69]
	v_mfma_f32_16x16x128_f8f6f4 v[58:61], v[196:203], v[42:49], v[58:61]
	v_mfma_f32_16x16x128_f8f6f4 v[50:53], v[204:211], v[42:49], v[50:53]
	s_setprio 0
	s_add_i32 s8, s8, 2
	s_addk_i32 s9, 0x100
	s_cmp_gt_u32 s8, 5
	s_barrier
	s_cbranch_scc1 .LBB0_766
	.p2align 6

.Lfw_4_b_p:
	s_barrier
	s_setprio 1
	v_mfma_f32_16x16x128_f8f6f4 v[54:57], v[122:129], v[66:73], 0
	v_mfma_f32_16x16x128_f8f6f4 v[238:241], v[190:197], v[66:73], 0
	v_mfma_f32_16x16x128_f8f6f4 v[242:245], v[122:129], v[74:81], 0
	v_mfma_f32_16x16x128_f8f6f4 v[246:249], v[190:197], v[74:81], 0
	v_mfma_f32_16x16x128_f8f6f4 v[250:253], v[122:129], v[82:89], 0
	v_mfma_f32_16x16x128_f8f6f4 v[130:133], v[190:197], v[82:89], 0
	v_mfma_f32_16x16x128_f8f6f4 v[66:69], v[122:129], v[90:97], 0
	v_mfma_f32_16x16x128_f8f6f4 v[190:193], v[190:197], v[90:97], 0
	s_setprio 0
	s_barrier
	s_nop 4
	ds_read_b128 v[2:5], v140
	ds_read_b128 v[6:9], v140 offset:1024
	ds_read_b128 v[10:13], v140 offset:2048
	ds_read_b128 v[14:17], v140 offset:3072
	s_mov_b32 m0, s28
	s_add_i32 s33, s87, 0x20000
	ds_read_b128 v[18:21], v138 offset:32768
	ds_read_b128 v[22:25], v138 offset:33792
	ds_read_b128 v[26:29], v138 offset:34816
	ds_read_b128 v[30:33], v138 offset:35840
	ds_read_b128 v[34:37], v138 offset:36864
	ds_read_b128 v[38:41], v138 offset:37888
	ds_read_b128 v[42:45], v138 offset:38912
	ds_read_b128 v[46:49], v138 offset:39936
	buffer_load_dwordx4 v1, s[44:47], s33 offen lds
	s_add_i32 s33, s87, 0x30000
	s_mov_b32 m0, s29
	s_nop 0
	buffer_load_dwordx4 v1, s[44:47], s33 offen lds
	s_waitcnt lgkmcnt(8)
	s_barrier
	s_waitcnt lgkmcnt(0)
	s_setprio 1
	s_waitcnt lgkmcnt(6)
	v_mfma_f32_16x16x128_f8f6f4 v[126:129], v[2:9], v[18:25], v[198:201]
	v_mfma_f32_16x16x128_f8f6f4 v[122:125], v[10:17], v[18:25], v[202:205]
	s_waitcnt lgkmcnt(4)
	v_mfma_f32_16x16x128_f8f6f4 v[114:117], v[2:9], v[26:33], v[114:117]
	v_mfma_f32_16x16x128_f8f6f4 v[106:109], v[10:17], v[26:33], v[106:109]
	s_waitcnt lgkmcnt(2)
	v_mfma_f32_16x16x128_f8f6f4 v[98:101], v[2:9], v[34:41], v[98:101]
	v_mfma_f32_16x16x128_f8f6f4 v[90:93], v[10:17], v[34:41], v[206:209]
	s_waitcnt lgkmcnt(0)
	v_mfma_f32_16x16x128_f8f6f4 v[82:85], v[2:9], v[42:49], v[210:213]
	v_mfma_f32_16x16x128_f8f6f4 v[74:77], v[10:17], v[42:49], v[214:217]
	s_setprio 0
	s_barrier
	s_mov_b32 m0, s31
	s_add_i32 s33, s86, 0x80
	ds_read_b128 v[142:145], v141
	ds_read_b128 v[146:149], v141 offset:1024
	ds_read_b128 v[150:153], v141 offset:2048
	ds_read_b128 v[154:157], v141 offset:3072
	buffer_load_dwordx4 v134, s[8:11], s33 offen lds
	s_add_i32 s33, s86, 0x20080
	s_mov_b32 m0, s34
	s_nop 0
	buffer_load_dwordx4 v134, s[8:11], s33 offen lds
	s_waitcnt vmcnt(10)
	s_barrier
	s_waitcnt lgkmcnt(0)
	s_setprio 1
	s_waitcnt lgkmcnt(2)
	v_mfma_f32_16x16x128_f8f6f4 v[118:121], v[142:149], v[18:25], v[118:121]
	s_waitcnt lgkmcnt(0)
	v_mfma_f32_16x16x128_f8f6f4 v[110:113], v[150:157], v[18:25], v[110:113]
	v_mfma_f32_16x16x128_f8f6f4 v[102:105], v[142:149], v[26:33], v[102:105]
	v_mfma_f32_16x16x128_f8f6f4 v[94:97], v[150:157], v[26:33], v[158:161]
	v_mfma_f32_16x16x128_f8f6f4 v[86:89], v[142:149], v[34:41], v[162:165]
	v_mfma_f32_16x16x128_f8f6f4 v[78:81], v[150:157], v[34:41], v[166:169]
	v_mfma_f32_16x16x128_f8f6f4 v[70:73], v[142:149], v[42:49], v[170:173]
	v_mfma_f32_16x16x128_f8f6f4 v[18:21], v[150:157], v[42:49], v[174:177]
	s_setprio 0
	s_mov_b32 m0, s35
	s_barrier
	ds_read_b128 v[158:161], v138 offset:49152
	ds_read_b128 v[162:165], v138 offset:50176
	ds_read_b128 v[166:169], v138 offset:51200
	ds_read_b128 v[170:173], v138 offset:52224
	ds_read_b128 v[174:177], v138 offset:53248
	ds_read_b128 v[178:181], v138 offset:54272
	ds_read_b128 v[182:185], v138 offset:55296
	ds_read_b128 v[186:189], v138 offset:56320
	buffer_load_dwordx4 v1, s[44:47], s88 offen lds
	s_add_i32 s87, s87, 0x10800
	s_mov_b32 m0, s36
	s_nop 0
	buffer_load_dwordx4 v1, s[44:47], s87 offen lds
	s_barrier
	s_waitcnt lgkmcnt(0)
	s_setprio 1
	s_waitcnt lgkmcnt(6)
	v_mfma_f32_16x16x128_f8f6f4 v[62:65], v[2:9], v[158:165], v[62:65]
	v_mfma_f32_16x16x128_f8f6f4 v[58:61], v[10:17], v[158:165], v[58:61]
	s_waitcnt lgkmcnt(4)
	v_mfma_f32_16x16x128_f8f6f4 v[50:53], v[2:9], v[166:173], v[50:53]
	v_mfma_f32_16x16x128_f8f6f4 v[42:45], v[10:17], v[166:173], v[218:221]
	s_waitcnt lgkmcnt(2)
	v_mfma_f32_16x16x128_f8f6f4 v[34:37], v[2:9], v[174:181], v[222:225]
	v_mfma_f32_16x16x128_f8f6f4 v[26:29], v[10:17], v[174:181], v[226:229]
	s_waitcnt lgkmcnt(0)
	v_mfma_f32_16x16x128_f8f6f4 v[230:233], v[2:9], v[182:189], v[230:233]
	v_mfma_f32_16x16x128_f8f6f4 v[10:13], v[10:17], v[182:189], v[234:237]
	s_setprio 0
	s_barrier
	s_mov_b32 m0, s37
	s_add_i32 s33, s86, 0x2080
	buffer_load_dwordx4 v134, s[8:11], s33 offen lds
	s_add_i32 s86, s86, 0x22080
	s_mov_b32 m0, s38
	s_nop 0
	buffer_load_dwordx4 v134, s[8:11], s86 offen lds
	s_waitcnt vmcnt(6)
	s_barrier
	s_setprio 1
	v_mfma_f32_16x16x128_f8f6f4 v[54:57], v[142:149], v[158:165], v[54:57]
	v_mfma_f32_16x16x128_f8f6f4 v[46:49], v[150:157], v[158:165], v[238:241]
	v_mfma_f32_16x16x128_f8f6f4 v[38:41], v[142:149], v[166:173], v[242:245]
	v_mfma_f32_16x16x128_f8f6f4 v[30:33], v[150:157], v[166:173], v[246:249]
	v_mfma_f32_16x16x128_f8f6f4 v[22:25], v[142:149], v[174:181], v[250:253]
	v_mfma_f32_16x16x128_f8f6f4 v[14:17], v[150:157], v[174:181], v[130:133]
	v_mfma_f32_16x16x128_f8f6f4 v[6:9], v[142:149], v[182:189], v[66:69]
	v_mfma_f32_16x16x128_f8f6f4 v[2:5], v[150:157], v[182:189], v[190:193]
	s_setprio 0
	s_add_i32 s79, s79, 2
	s_addk_i32 s7, 0x1000
	s_addk_i32 s78, 0x100
	s_cmp_gt_u32 s79, 5
	s_barrier
	.p2align 6

.Lfw_5_b_p:
	s_barrier
	s_setprio 1
	v_mfma_f32_16x16x32_bf16 v[50:53], v[190:193], v[158:161], 0
	v_mfma_f32_16x16x32_bf16 v[42:45], v[198:201], v[158:161], 0
	v_mfma_f32_16x16x32_bf16 v[34:37], v[190:193], v[166:169], 0
	v_mfma_f32_16x16x32_bf16 v[26:29], v[198:201], v[166:169], 0
	v_mfma_f32_16x16x32_bf16 v[18:21], v[190:193], v[174:177], 0
	v_mfma_f32_16x16x32_bf16 v[10:13], v[198:201], v[174:177], 0
	v_mfma_f32_16x16x32_bf16 v[6:9], v[190:193], v[182:185], 0
	v_mfma_f32_16x16x32_bf16 v[2:5], v[198:201], v[182:185], 0
	v_mfma_f32_16x16x32_bf16 v[50:53], v[194:197], v[162:165], v[50:53]
	v_mfma_f32_16x16x32_bf16 v[42:45], v[202:205], v[162:165], v[42:45]
	v_mfma_f32_16x16x32_bf16 v[34:37], v[194:197], v[170:173], v[34:37]
	v_mfma_f32_16x16x32_bf16 v[26:29], v[202:205], v[170:173], v[26:29]
	v_mfma_f32_16x16x32_bf16 v[18:21], v[194:197], v[178:181], v[18:21]
	v_mfma_f32_16x16x32_bf16 v[10:13], v[202:205], v[178:181], v[10:13]
	v_mfma_f32_16x16x32_bf16 v[6:9], v[194:197], v[186:189], v[6:9]
	v_mfma_f32_16x16x32_bf16 v[2:5], v[202:205], v[186:189], v[2:5]
	s_setprio 0
	s_barrier
	ds_read_b128 v[134:137], v144
	ds_read_b128 v[146:149], v144 offset:1024
	ds_read_b128 v[150:153], v144 offset:2048
	ds_read_b128 v[154:157], v144 offset:3072
	s_mov_b32 m0, s20
	s_add_i32 s33, s50, 0x40000
	ds_read_b128 v[158:161], v142 offset:32768
	ds_read_b128 v[162:165], v142 offset:33792
	ds_read_b128 v[166:169], v142 offset:34816
	ds_read_b128 v[170:173], v142 offset:35840
	ds_read_b128 v[174:177], v142 offset:36864
	ds_read_b128 v[178:181], v142 offset:37888
	ds_read_b128 v[182:185], v142 offset:38912
	ds_read_b128 v[186:189], v142 offset:39936
	buffer_load_dwordx4 v1, s[40:43], s33 offen lds
	s_add_i32 s33, s50, 0x60000
	s_mov_b32 m0, s21
	s_nop 0
	buffer_load_dwordx4 v1, s[40:43], s33 offen lds
	s_waitcnt lgkmcnt(8)
	s_barrier
	s_waitcnt lgkmcnt(0)
	s_setprio 1
	s_waitcnt lgkmcnt(7)
	v_mfma_f32_16x16x32_bf16 v[126:129], v[134:137], v[158:161], v[126:129]
	v_mfma_f32_16x16x32_bf16 v[122:125], v[150:153], v[158:161], v[122:125]
	s_waitcnt lgkmcnt(5)
	v_mfma_f32_16x16x32_bf16 v[118:121], v[134:137], v[166:169], v[118:121]
	v_mfma_f32_16x16x32_bf16 v[110:113], v[150:153], v[166:169], v[110:113]
	s_waitcnt lgkmcnt(3)
	v_mfma_f32_16x16x32_bf16 v[102:105], v[134:137], v[174:177], v[102:105]
	v_mfma_f32_16x16x32_bf16 v[94:97], v[150:153], v[174:177], v[94:97]
	s_waitcnt lgkmcnt(1)
	v_mfma_f32_16x16x32_bf16 v[86:89], v[134:137], v[182:185], v[86:89]
	v_mfma_f32_16x16x32_bf16 v[78:81], v[150:153], v[182:185], v[78:81]
	v_mfma_f32_16x16x32_bf16 v[126:129], v[146:149], v[162:165], v[126:129]
	v_mfma_f32_16x16x32_bf16 v[122:125], v[154:157], v[162:165], v[122:125]
	v_mfma_f32_16x16x32_bf16 v[118:121], v[146:149], v[170:173], v[118:121]
	v_mfma_f32_16x16x32_bf16 v[110:113], v[154:157], v[170:173], v[110:113]
	v_mfma_f32_16x16x32_bf16 v[102:105], v[146:149], v[178:181], v[102:105]
	v_mfma_f32_16x16x32_bf16 v[94:97], v[154:157], v[178:181], v[94:97]
	s_waitcnt lgkmcnt(0)
	v_mfma_f32_16x16x32_bf16 v[86:89], v[146:149], v[186:189], v[86:89]
	v_mfma_f32_16x16x32_bf16 v[78:81], v[154:157], v[186:189], v[78:81]
	s_setprio 0
	s_barrier
	s_mov_b32 m0, s23
	s_or_b32 s33, s49, 0x80
	ds_read_b128 v[190:193], v145
	ds_read_b128 v[194:197], v145 offset:1024
	ds_read_b128 v[198:201], v145 offset:2048
	ds_read_b128 v[202:205], v145 offset:3072
	buffer_load_dwordx4 v138, s[8:11], s33 offen lds
	s_add_i32 s33, s49, 0x20080
	s_mov_b32 m0, s24
	s_nop 0
	buffer_load_dwordx4 v138, s[8:11], s33 offen lds
	s_waitcnt vmcnt(10)
	s_barrier
	s_waitcnt lgkmcnt(0)
	s_setprio 1
	s_waitcnt lgkmcnt(3)
	v_mfma_f32_16x16x32_bf16 v[114:117], v[190:193], v[158:161], v[114:117]
	s_waitcnt lgkmcnt(1)
	v_mfma_f32_16x16x32_bf16 v[106:109], v[198:201], v[158:161], v[106:109]
	v_mfma_f32_16x16x32_bf16 v[98:101], v[190:193], v[166:169], v[98:101]
	v_mfma_f32_16x16x32_bf16 v[90:93], v[198:201], v[166:169], v[90:93]
	v_mfma_f32_16x16x32_bf16 v[82:85], v[190:193], v[174:177], v[82:85]
	v_mfma_f32_16x16x32_bf16 v[74:77], v[198:201], v[174:177], v[74:77]
	v_mfma_f32_16x16x32_bf16 v[70:73], v[190:193], v[182:185], v[70:73]
	v_mfma_f32_16x16x32_bf16 v[66:69], v[198:201], v[182:185], v[66:69]
	v_mfma_f32_16x16x32_bf16 v[114:117], v[194:197], v[162:165], v[114:117]
	s_waitcnt lgkmcnt(0)
	v_mfma_f32_16x16x32_bf16 v[106:109], v[202:205], v[162:165], v[106:109]
	v_mfma_f32_16x16x32_bf16 v[98:101], v[194:197], v[170:173], v[98:101]
	v_mfma_f32_16x16x32_bf16 v[90:93], v[202:205], v[170:173], v[90:93]
	v_mfma_f32_16x16x32_bf16 v[82:85], v[194:197], v[178:181], v[82:85]
	v_mfma_f32_16x16x32_bf16 v[74:77], v[202:205], v[178:181], v[74:77]
	v_mfma_f32_16x16x32_bf16 v[70:73], v[194:197], v[186:189], v[70:73]
	v_mfma_f32_16x16x32_bf16 v[66:69], v[202:205], v[186:189], v[66:69]
	s_setprio 0
	s_mov_b32 m0, s25
	s_barrier
	ds_read_b128 v[158:161], v142 offset:49152
	ds_read_b128 v[162:165], v142 offset:50176
	ds_read_b128 v[166:169], v142 offset:51200
	ds_read_b128 v[170:173], v142 offset:52224
	ds_read_b128 v[174:177], v142 offset:53248
	ds_read_b128 v[178:181], v142 offset:54272
	ds_read_b128 v[182:185], v142 offset:55296
	ds_read_b128 v[186:189], v142 offset:56320
	buffer_load_dwordx4 v1, s[40:43], s51 offen lds
	s_add_i32 s50, s50, 0x20080
	s_mov_b32 m0, s26
	s_nop 0
	buffer_load_dwordx4 v1, s[40:43], s50 offen lds
	s_barrier
	s_waitcnt lgkmcnt(0)
	s_setprio 1
	s_waitcnt lgkmcnt(7)
	v_mfma_f32_16x16x32_bf16 v[62:65], v[134:137], v[158:161], v[62:65]
	v_mfma_f32_16x16x32_bf16 v[58:61], v[150:153], v[158:161], v[58:61]
	s_waitcnt lgkmcnt(5)
	v_mfma_f32_16x16x32_bf16 v[54:57], v[134:137], v[166:169], v[54:57]
	v_mfma_f32_16x16x32_bf16 v[46:49], v[150:153], v[166:169], v[46:49]
	s_waitcnt lgkmcnt(3)
	v_mfma_f32_16x16x32_bf16 v[38:41], v[134:137], v[174:177], v[38:41]
	v_mfma_f32_16x16x32_bf16 v[30:33], v[150:153], v[174:177], v[30:33]
	s_waitcnt lgkmcnt(1)
	v_mfma_f32_16x16x32_bf16 v[22:25], v[134:137], v[182:185], v[22:25]
	v_mfma_f32_16x16x32_bf16 v[14:17], v[150:153], v[182:185], v[14:17]
	v_mfma_f32_16x16x32_bf16 v[62:65], v[146:149], v[162:165], v[62:65]
	v_mfma_f32_16x16x32_bf16 v[58:61], v[154:157], v[162:165], v[58:61]
	v_mfma_f32_16x16x32_bf16 v[54:57], v[146:149], v[170:173], v[54:57]
	v_mfma_f32_16x16x32_bf16 v[46:49], v[154:157], v[170:173], v[46:49]
	v_mfma_f32_16x16x32_bf16 v[38:41], v[146:149], v[178:181], v[38:41]
	v_mfma_f32_16x16x32_bf16 v[30:33], v[154:157], v[178:181], v[30:33]
	s_waitcnt lgkmcnt(0)
	v_mfma_f32_16x16x32_bf16 v[22:25], v[146:149], v[186:189], v[22:25]
	v_mfma_f32_16x16x32_bf16 v[14:17], v[154:157], v[186:189], v[14:17]
	s_setprio 0
	s_barrier
	s_mov_b32 m0, s27
	s_add_i32 s33, s49, 0x40080
	buffer_load_dwordx4 v138, s[8:11], s33 offen lds
	s_add_i32 s49, s49, 0x60080
	s_mov_b32 m0, s28
	s_nop 0
	buffer_load_dwordx4 v138, s[8:11], s49 offen lds
	s_waitcnt vmcnt(6)
	s_barrier
	s_setprio 1
	v_mfma_f32_16x16x32_bf16 v[50:53], v[190:193], v[158:161], v[50:53]
	v_mfma_f32_16x16x32_bf16 v[42:45], v[198:201], v[158:161], v[42:45]
	v_mfma_f32_16x16x32_bf16 v[34:37], v[190:193], v[166:169], v[34:37]
	v_mfma_f32_16x16x32_bf16 v[26:29], v[198:201], v[166:169], v[26:29]
	v_mfma_f32_16x16x32_bf16 v[18:21], v[190:193], v[174:177], v[18:21]
	v_mfma_f32_16x16x32_bf16 v[10:13], v[198:201], v[174:177], v[10:13]
	v_mfma_f32_16x16x32_bf16 v[6:9], v[190:193], v[182:185], v[6:9]
	v_mfma_f32_16x16x32_bf16 v[2:5], v[198:201], v[182:185], v[2:5]
	v_mfma_f32_16x16x32_bf16 v[50:53], v[194:197], v[162:165], v[50:53]
	v_mfma_f32_16x16x32_bf16 v[42:45], v[202:205], v[162:165], v[42:45]
	v_mfma_f32_16x16x32_bf16 v[34:37], v[194:197], v[170:173], v[34:37]
	v_mfma_f32_16x16x32_bf16 v[26:29], v[202:205], v[170:173], v[26:29]
	v_mfma_f32_16x16x32_bf16 v[18:21], v[194:197], v[178:181], v[18:21]
	v_mfma_f32_16x16x32_bf16 v[10:13], v[202:205], v[178:181], v[10:13]
	v_mfma_f32_16x16x32_bf16 v[6:9], v[194:197], v[186:189], v[6:9]
	v_mfma_f32_16x16x32_bf16 v[2:5], v[202:205], v[186:189], v[2:5]
	s_setprio 0
	s_add_i32 s47, s47, 2
	s_addk_i32 s7, 0x100
	s_addk_i32 s46, 0x100
	s_cmp_gt_u32 s47, 13
	s_barrier
	.p2align 6

.Lfw_6_b_p:
	s_barrier
	s_setprio 1
	v_mfma_f32_16x16x32_bf16 v[54:57], v[178:181], v[146:149], 0
	v_mfma_f32_16x16x32_bf16 v[50:53], v[200:203], v[146:149], 0
	v_mfma_f32_16x16x32_bf16 v[38:41], v[178:181], v[154:157], 0
	v_mfma_f32_16x16x32_bf16 v[34:37], v[200:203], v[154:157], 0
	v_mfma_f32_16x16x32_bf16 v[22:25], v[178:181], v[162:165], 0
	v_mfma_f32_16x16x32_bf16 v[18:21], v[200:203], v[162:165], 0
	v_mfma_f32_16x16x32_bf16 v[6:9], v[178:181], v[170:173], 0
	v_mfma_f32_16x16x32_bf16 v[2:5], v[200:203], v[170:173], 0
	v_mfma_f32_16x16x32_bf16 v[54:57], v[182:185], v[150:153], v[54:57]
	v_mfma_f32_16x16x32_bf16 v[50:53], v[204:207], v[150:153], v[50:53]
	v_mfma_f32_16x16x32_bf16 v[38:41], v[182:185], v[158:161], v[38:41]
	v_mfma_f32_16x16x32_bf16 v[34:37], v[204:207], v[158:161], v[34:37]
	v_mfma_f32_16x16x32_bf16 v[22:25], v[182:185], v[166:169], v[22:25]
	v_mfma_f32_16x16x32_bf16 v[18:21], v[204:207], v[166:169], v[18:21]
	v_mfma_f32_16x16x32_bf16 v[6:9], v[182:185], v[174:177], v[6:9]
	v_mfma_f32_16x16x32_bf16 v[2:5], v[204:207], v[174:177], v[2:5]
	s_setprio 0
	s_barrier
	ds_read_b128 v[130:133], v198
	ds_read_b128 v[134:137], v198 offset:1024
	ds_read_b128 v[138:141], v198 offset:2048
	ds_read_b128 v[142:145], v198 offset:3072
	s_mov_b32 m0, s22
	s_add_i32 s33, s79, 0x40000
	ds_read_b128 v[146:149], v196 offset:32768
	ds_read_b128 v[150:153], v196 offset:33792
	ds_read_b128 v[154:157], v196 offset:34816
	ds_read_b128 v[158:161], v196 offset:35840
	ds_read_b128 v[162:165], v196 offset:36864
	ds_read_b128 v[166:169], v196 offset:37888
	ds_read_b128 v[170:173], v196 offset:38912
	ds_read_b128 v[174:177], v196 offset:39936
	buffer_load_dwordx4 v1, s[48:51], s33 offen lds
	s_add_i32 s33, s79, 0x60000
	s_mov_b32 m0, s23
	s_nop 0
	buffer_load_dwordx4 v1, s[48:51], s33 offen lds
	s_waitcnt lgkmcnt(8)
	s_barrier
	s_waitcnt lgkmcnt(0)
	s_setprio 1
	s_waitcnt lgkmcnt(7)
	v_mfma_f32_16x16x32_bf16 v[126:129], v[130:133], v[146:149], v[126:129]
	v_mfma_f32_16x16x32_bf16 v[122:125], v[138:141], v[146:149], v[122:125]
	s_waitcnt lgkmcnt(5)
	v_mfma_f32_16x16x32_bf16 v[110:113], v[130:133], v[154:157], v[110:113]
	v_mfma_f32_16x16x32_bf16 v[106:109], v[138:141], v[154:157], v[106:109]
	s_waitcnt lgkmcnt(3)
	v_mfma_f32_16x16x32_bf16 v[94:97], v[130:133], v[162:165], v[94:97]
	v_mfma_f32_16x16x32_bf16 v[90:93], v[138:141], v[162:165], v[90:93]
	s_waitcnt lgkmcnt(1)
	v_mfma_f32_16x16x32_bf16 v[78:81], v[130:133], v[170:173], v[78:81]
	v_mfma_f32_16x16x32_bf16 v[74:77], v[138:141], v[170:173], v[74:77]
	v_mfma_f32_16x16x32_bf16 v[126:129], v[134:137], v[150:153], v[126:129]
	v_mfma_f32_16x16x32_bf16 v[122:125], v[142:145], v[150:153], v[122:125]
	v_mfma_f32_16x16x32_bf16 v[110:113], v[134:137], v[158:161], v[110:113]
	v_mfma_f32_16x16x32_bf16 v[106:109], v[142:145], v[158:161], v[106:109]
	v_mfma_f32_16x16x32_bf16 v[94:97], v[134:137], v[166:169], v[94:97]
	v_mfma_f32_16x16x32_bf16 v[90:93], v[142:145], v[166:169], v[90:93]
	s_waitcnt lgkmcnt(0)
	v_mfma_f32_16x16x32_bf16 v[78:81], v[134:137], v[174:177], v[78:81]
	v_mfma_f32_16x16x32_bf16 v[74:77], v[142:145], v[174:177], v[74:77]
	s_setprio 0
	s_barrier
	s_mov_b32 m0, s29
	s_add_i32 s33, s78, 0x80
	ds_read_b128 v[178:181], v199
	ds_read_b128 v[182:185], v199 offset:1024
	ds_read_b128 v[200:203], v199 offset:2048
	ds_read_b128 v[204:207], v199 offset:3072
	buffer_load_dwordx4 v192, s[8:11], s33 offen lds
	s_add_i32 s33, s78, 0x20080
	s_mov_b32 m0, s30
	s_nop 0
	buffer_load_dwordx4 v192, s[8:11], s33 offen lds
	s_waitcnt vmcnt(10)
	s_barrier
	s_waitcnt lgkmcnt(0)
	s_setprio 1
	s_waitcnt lgkmcnt(3)
	v_mfma_f32_16x16x32_bf16 v[118:121], v[178:181], v[146:149], v[118:121]
	s_waitcnt lgkmcnt(1)
	v_mfma_f32_16x16x32_bf16 v[114:117], v[200:203], v[146:149], v[114:117]
	v_mfma_f32_16x16x32_bf16 v[102:105], v[178:181], v[154:157], v[102:105]
	v_mfma_f32_16x16x32_bf16 v[98:101], v[200:203], v[154:157], v[98:101]
	v_mfma_f32_16x16x32_bf16 v[86:89], v[178:181], v[162:165], v[86:89]
	v_mfma_f32_16x16x32_bf16 v[82:85], v[200:203], v[162:165], v[82:85]
	v_mfma_f32_16x16x32_bf16 v[70:73], v[178:181], v[170:173], v[70:73]
	v_mfma_f32_16x16x32_bf16 v[66:69], v[200:203], v[170:173], v[66:69]
	v_mfma_f32_16x16x32_bf16 v[118:121], v[182:185], v[150:153], v[118:121]
	s_waitcnt lgkmcnt(0)
	v_mfma_f32_16x16x32_bf16 v[114:117], v[204:207], v[150:153], v[114:117]
	v_mfma_f32_16x16x32_bf16 v[102:105], v[182:185], v[158:161], v[102:105]
	v_mfma_f32_16x16x32_bf16 v[98:101], v[204:207], v[158:161], v[98:101]
	v_mfma_f32_16x16x32_bf16 v[86:89], v[182:185], v[166:169], v[86:89]
	v_mfma_f32_16x16x32_bf16 v[82:85], v[204:207], v[166:169], v[82:85]
	v_mfma_f32_16x16x32_bf16 v[70:73], v[182:185], v[174:177], v[70:73]
	v_mfma_f32_16x16x32_bf16 v[66:69], v[204:207], v[174:177], v[66:69]
	s_setprio 0
	s_mov_b32 m0, s31
	s_barrier
	ds_read_b128 v[146:149], v196 offset:49152
	ds_read_b128 v[150:153], v196 offset:50176
	ds_read_b128 v[154:157], v196 offset:51200
	ds_read_b128 v[158:161], v196 offset:52224
	ds_read_b128 v[162:165], v196 offset:53248
	ds_read_b128 v[166:169], v196 offset:54272
	ds_read_b128 v[170:173], v196 offset:55296
	ds_read_b128 v[174:177], v196 offset:56320
	buffer_load_dwordx4 v1, s[48:51], s84 offen lds
	s_add_i32 s79, s79, 0x20080
	s_mov_b32 m0, s34
	s_nop 0
	buffer_load_dwordx4 v1, s[48:51], s79 offen lds
	s_barrier
	s_waitcnt lgkmcnt(0)
	s_setprio 1
	s_waitcnt lgkmcnt(7)
	v_mfma_f32_16x16x32_bf16 v[62:65], v[130:133], v[146:149], v[62:65]
	v_mfma_f32_16x16x32_bf16 v[58:61], v[138:141], v[146:149], v[58:61]
	s_waitcnt lgkmcnt(5)
	v_mfma_f32_16x16x32_bf16 v[46:49], v[130:133], v[154:157], v[46:49]
	v_mfma_f32_16x16x32_bf16 v[42:45], v[138:141], v[154:157], v[42:45]
	s_waitcnt lgkmcnt(3)
	v_mfma_f32_16x16x32_bf16 v[30:33], v[130:133], v[162:165], v[30:33]
	v_mfma_f32_16x16x32_bf16 v[26:29], v[138:141], v[162:165], v[26:29]
	s_waitcnt lgkmcnt(1)
	v_mfma_f32_16x16x32_bf16 v[14:17], v[130:133], v[170:173], v[14:17]
	v_mfma_f32_16x16x32_bf16 v[10:13], v[138:141], v[170:173], v[10:13]
	v_mfma_f32_16x16x32_bf16 v[62:65], v[134:137], v[150:153], v[62:65]
	v_mfma_f32_16x16x32_bf16 v[58:61], v[142:145], v[150:153], v[58:61]
	v_mfma_f32_16x16x32_bf16 v[46:49], v[134:137], v[158:161], v[46:49]
	v_mfma_f32_16x16x32_bf16 v[42:45], v[142:145], v[158:161], v[42:45]
	v_mfma_f32_16x16x32_bf16 v[30:33], v[134:137], v[166:169], v[30:33]
	v_mfma_f32_16x16x32_bf16 v[26:29], v[142:145], v[166:169], v[26:29]
	s_waitcnt lgkmcnt(0)
	v_mfma_f32_16x16x32_bf16 v[14:17], v[134:137], v[174:177], v[14:17]
	v_mfma_f32_16x16x32_bf16 v[10:13], v[142:145], v[174:177], v[10:13]
	s_setprio 0
	s_barrier
	s_mov_b32 m0, s35
	s_add_i32 s33, s78, 0x40080
	buffer_load_dwordx4 v192, s[8:11], s33 offen lds
	s_add_i32 s78, s78, 0x60080
	s_mov_b32 m0, s36
	s_nop 0
	buffer_load_dwordx4 v192, s[8:11], s78 offen lds
	s_waitcnt vmcnt(6)
	s_barrier
	s_setprio 1
	v_mfma_f32_16x16x32_bf16 v[54:57], v[178:181], v[146:149], v[54:57]
	v_mfma_f32_16x16x32_bf16 v[50:53], v[200:203], v[146:149], v[50:53]
	v_mfma_f32_16x16x32_bf16 v[38:41], v[178:181], v[154:157], v[38:41]
	v_mfma_f32_16x16x32_bf16 v[34:37], v[200:203], v[154:157], v[34:37]
	v_mfma_f32_16x16x32_bf16 v[22:25], v[178:181], v[162:165], v[22:25]
	v_mfma_f32_16x16x32_bf16 v[18:21], v[200:203], v[162:165], v[18:21]
	v_mfma_f32_16x16x32_bf16 v[6:9], v[178:181], v[170:173], v[6:9]
	v_mfma_f32_16x16x32_bf16 v[2:5], v[200:203], v[170:173], v[2:5]
	v_mfma_f32_16x16x32_bf16 v[54:57], v[182:185], v[150:153], v[54:57]
	v_mfma_f32_16x16x32_bf16 v[50:53], v[204:207], v[150:153], v[50:53]
	v_mfma_f32_16x16x32_bf16 v[38:41], v[182:185], v[158:161], v[38:41]
	v_mfma_f32_16x16x32_bf16 v[34:37], v[204:207], v[158:161], v[34:37]
	v_mfma_f32_16x16x32_bf16 v[22:25], v[182:185], v[166:169], v[22:25]
	v_mfma_f32_16x16x32_bf16 v[18:21], v[204:207], v[166:169], v[18:21]
	v_mfma_f32_16x16x32_bf16 v[6:9], v[182:185], v[174:177], v[6:9]
	v_mfma_f32_16x16x32_bf16 v[2:5], v[204:207], v[174:177], v[2:5]
	s_setprio 0
	s_add_i32 s13, s13, 2
	s_addk_i32 s7, 0x100
	s_addk_i32 s12, 0x100
	s_cmp_gt_u32 s13, 13
	s_barrier
	.p2align 6

.Lfw_7_b:
	s_barrier
	s_setprio 1
	v_mfma_f32_16x16x128_f8f6f4 v[106:109], v[198:205], v[18:25], v[106:109]
	v_mfma_f32_16x16x128_f8f6f4 v[98:101], v[206:213], v[18:25], v[98:101]
	v_mfma_f32_16x16x128_f8f6f4 v[90:93], v[198:205], v[26:33], v[90:93]
	v_mfma_f32_16x16x128_f8f6f4 v[82:85], v[206:213], v[26:33], v[82:85]
	v_mfma_f32_16x16x128_f8f6f4 v[74:77], v[198:205], v[34:41], v[74:77]
	v_mfma_f32_16x16x128_f8f6f4 v[66:69], v[206:213], v[34:41], v[66:69]
	v_mfma_f32_16x16x128_f8f6f4 v[58:61], v[198:205], v[42:49], v[58:61]
	v_mfma_f32_16x16x128_f8f6f4 v[50:53], v[206:213], v[42:49], v[50:53]
	s_setprio 0
	v_add_u32_e32 v14, 0x18000, v189
	s_barrier
	ds_read_b128 v[2:5], v14
	ds_read_b128 v[6:9], v14 offset:1024
	ds_read_b128 v[10:13], v14 offset:2048
	ds_read_b128 v[14:17], v14 offset:3072
	s_mov_b32 m0, s23
	ds_read_b128 v[18:21], v191 offset:32768
	ds_read_b128 v[22:25], v191 offset:33792
	ds_read_b128 v[26:29], v191 offset:34816
	ds_read_b128 v[30:33], v191 offset:35840
	ds_read_b128 v[34:37], v191 offset:36864
	ds_read_b128 v[38:41], v191 offset:37888
	ds_read_b128 v[42:45], v191 offset:38912
	ds_read_b128 v[46:49], v191 offset:39936
	buffer_load_dwordx4 v196, s[40:43], s59 offen lds
	s_mov_b32 m0, s24
	s_nop 0
	buffer_load_dwordx4 v197, s[40:43], s59 offen lds
	s_waitcnt lgkmcnt(8)
	s_barrier
	s_waitcnt lgkmcnt(0)
	s_setprio 1
	s_waitcnt lgkmcnt(6)
	v_mfma_f32_16x16x128_f8f6f4 v[174:177], v[2:9], v[18:25], v[174:177]
	v_mfma_f32_16x16x128_f8f6f4 v[166:169], v[10:17], v[18:25], v[166:169]
	s_waitcnt lgkmcnt(4)
	v_mfma_f32_16x16x128_f8f6f4 v[158:161], v[2:9], v[26:33], v[158:161]
	v_mfma_f32_16x16x128_f8f6f4 v[150:153], v[10:17], v[26:33], v[150:153]
	s_waitcnt lgkmcnt(2)
	v_mfma_f32_16x16x128_f8f6f4 v[142:145], v[2:9], v[34:41], v[142:145]
	v_mfma_f32_16x16x128_f8f6f4 v[134:137], v[10:17], v[34:41], v[134:137]
	s_waitcnt lgkmcnt(0)
	v_mfma_f32_16x16x128_f8f6f4 v[126:129], v[2:9], v[42:49], v[126:129]
	v_mfma_f32_16x16x128_f8f6f4 v[118:121], v[10:17], v[42:49], v[118:121]
	s_setprio 0
	s_barrier
	s_mov_b32 m0, s26
	v_add_u32_e32 v208, 0x1c000, v189
	ds_read_b128 v[196:199], v208
	ds_read_b128 v[200:203], v208 offset:1024
	ds_read_b128 v[204:207], v208 offset:2048
	ds_read_b128 v[208:211], v208 offset:3072
	buffer_load_dwordx4 v184, s[12:15], s7 offen lds
	s_add_i32 s7, s6, 0x10080
	s_mov_b32 m0, s27
	s_nop 0
	buffer_load_dwordx4 v184, s[12:15], s7 offen lds
	s_waitcnt vmcnt(10)
	s_barrier
	s_waitcnt lgkmcnt(0)
	s_setprio 1
	s_waitcnt lgkmcnt(2)
	v_mfma_f32_16x16x128_f8f6f4 v[170:173], v[196:203], v[18:25], v[170:173]
	s_waitcnt lgkmcnt(0)
	v_mfma_f32_16x16x128_f8f6f4 v[162:165], v[204:211], v[18:25], v[162:165]
	v_mfma_f32_16x16x128_f8f6f4 v[154:157], v[196:203], v[26:33], v[154:157]
	v_mfma_f32_16x16x128_f8f6f4 v[146:149], v[204:211], v[26:33], v[146:149]
	v_mfma_f32_16x16x128_f8f6f4 v[138:141], v[196:203], v[34:41], v[138:141]
	v_mfma_f32_16x16x128_f8f6f4 v[130:133], v[204:211], v[34:41], v[130:133]
	v_mfma_f32_16x16x128_f8f6f4 v[122:125], v[196:203], v[42:49], v[122:125]
	v_mfma_f32_16x16x128_f8f6f4 v[114:117], v[204:211], v[42:49], v[114:117]
	s_setprio 0
	s_mov_b32 m0, s28
	s_barrier
	ds_read_b128 v[18:21], v191 offset:49152
	ds_read_b128 v[22:25], v191 offset:50176
	ds_read_b128 v[26:29], v191 offset:51200
	ds_read_b128 v[30:33], v191 offset:52224
	ds_read_b128 v[34:37], v191 offset:53248
	ds_read_b128 v[38:41], v191 offset:54272
	ds_read_b128 v[42:45], v191 offset:55296
	ds_read_b128 v[46:49], v191 offset:56320
	buffer_load_dwordx4 v214, s[40:43], s58 offen lds
	s_mov_b32 m0, s29
	s_nop 0
	buffer_load_dwordx4 v215, s[40:43], s58 offen lds
	s_barrier
	s_waitcnt lgkmcnt(0)
	s_setprio 1
	s_waitcnt lgkmcnt(6)
	v_mfma_f32_16x16x128_f8f6f4 v[110:113], v[2:9], v[18:25], v[110:113]
	v_mfma_f32_16x16x128_f8f6f4 v[102:105], v[10:17], v[18:25], v[102:105]
	s_waitcnt lgkmcnt(4)
	v_mfma_f32_16x16x128_f8f6f4 v[94:97], v[2:9], v[26:33], v[94:97]
	v_mfma_f32_16x16x128_f8f6f4 v[86:89], v[10:17], v[26:33], v[86:89]
	s_waitcnt lgkmcnt(2)
	v_mfma_f32_16x16x128_f8f6f4 v[78:81], v[2:9], v[34:41], v[78:81]
	v_mfma_f32_16x16x128_f8f6f4 v[70:73], v[10:17], v[34:41], v[70:73]
	s_waitcnt lgkmcnt(0)
	v_mfma_f32_16x16x128_f8f6f4 v[62:65], v[2:9], v[42:49], v[62:65]
	v_mfma_f32_16x16x128_f8f6f4 v[54:57], v[10:17], v[42:49], v[54:57]
	s_setprio 0
	s_barrier
	s_mov_b32 m0, s30
	s_add_i32 s7, s6, 0x20080
	buffer_load_dwordx4 v184, s[12:15], s7 offen lds
	s_add_i32 s6, s6, 0x30080
	s_mov_b32 m0, s31
	s_nop 0
	buffer_load_dwordx4 v184, s[12:15], s6 offen lds
	s_waitcnt vmcnt(6)
	s_barrier
	s_setprio 1
	v_mfma_f32_16x16x128_f8f6f4 v[106:109], v[196:203], v[18:25], v[106:109]
	v_mfma_f32_16x16x128_f8f6f4 v[98:101], v[204:211], v[18:25], v[98:101]
	v_mfma_f32_16x16x128_f8f6f4 v[90:93], v[196:203], v[26:33], v[90:93]
	v_mfma_f32_16x16x128_f8f6f4 v[82:85], v[204:211], v[26:33], v[82:85]
	v_mfma_f32_16x16x128_f8f6f4 v[74:77], v[196:203], v[34:41], v[74:77]
	v_mfma_f32_16x16x128_f8f6f4 v[66:69], v[204:211], v[34:41], v[66:69]
	v_mfma_f32_16x16x128_f8f6f4 v[58:61], v[196:203], v[42:49], v[58:61]
	v_mfma_f32_16x16x128_f8f6f4 v[50:53], v[204:211], v[42:49], v[50:53]
	s_setprio 0
	s_add_i32 s8, s8, 2
	s_addk_i32 s9, 0x100
	s_cmp_gt_u32 s8, 5
	s_barrier
	s_cbranch_scc1 .LBB0_1650
	.p2align 6

.Lfw_8_b_p:
	s_barrier
	s_setprio 1
	v_mfma_f32_16x16x128_f8f6f4 v[54:57], v[122:129], v[66:73], 0
	v_mfma_f32_16x16x128_f8f6f4 v[238:241], v[190:197], v[66:73], 0
	v_mfma_f32_16x16x128_f8f6f4 v[242:245], v[122:129], v[74:81], 0
	v_mfma_f32_16x16x128_f8f6f4 v[246:249], v[190:197], v[74:81], 0
	v_mfma_f32_16x16x128_f8f6f4 v[250:253], v[122:129], v[82:89], 0
	v_mfma_f32_16x16x128_f8f6f4 v[130:133], v[190:197], v[82:89], 0
	v_mfma_f32_16x16x128_f8f6f4 v[66:69], v[122:129], v[90:97], 0
	v_mfma_f32_16x16x128_f8f6f4 v[190:193], v[190:197], v[90:97], 0
	s_setprio 0
	s_barrier
	s_nop 4
	ds_read_b128 v[2:5], v140
	ds_read_b128 v[6:9], v140 offset:1024
	ds_read_b128 v[10:13], v140 offset:2048
	ds_read_b128 v[14:17], v140 offset:3072
	s_mov_b32 m0, s28
	s_add_i32 s33, s87, 0x20000
	ds_read_b128 v[18:21], v138 offset:32768
	ds_read_b128 v[22:25], v138 offset:33792
	ds_read_b128 v[26:29], v138 offset:34816
	ds_read_b128 v[30:33], v138 offset:35840
	ds_read_b128 v[34:37], v138 offset:36864
	ds_read_b128 v[38:41], v138 offset:37888
	ds_read_b128 v[42:45], v138 offset:38912
	ds_read_b128 v[46:49], v138 offset:39936
	buffer_load_dwordx4 v1, s[44:47], s33 offen lds
	s_add_i32 s33, s87, 0x30000
	s_mov_b32 m0, s29
	s_nop 0
	buffer_load_dwordx4 v1, s[44:47], s33 offen lds
	s_waitcnt lgkmcnt(8)
	s_barrier
	s_waitcnt lgkmcnt(0)
	s_setprio 1
	s_waitcnt lgkmcnt(6)
	v_mfma_f32_16x16x128_f8f6f4 v[126:129], v[2:9], v[18:25], v[198:201]
	v_mfma_f32_16x16x128_f8f6f4 v[122:125], v[10:17], v[18:25], v[202:205]
	s_waitcnt lgkmcnt(4)
	v_mfma_f32_16x16x128_f8f6f4 v[114:117], v[2:9], v[26:33], v[114:117]
	v_mfma_f32_16x16x128_f8f6f4 v[106:109], v[10:17], v[26:33], v[106:109]
	s_waitcnt lgkmcnt(2)
	v_mfma_f32_16x16x128_f8f6f4 v[98:101], v[2:9], v[34:41], v[98:101]
	v_mfma_f32_16x16x128_f8f6f4 v[90:93], v[10:17], v[34:41], v[206:209]
	s_waitcnt lgkmcnt(0)
	v_mfma_f32_16x16x128_f8f6f4 v[82:85], v[2:9], v[42:49], v[210:213]
	v_mfma_f32_16x16x128_f8f6f4 v[74:77], v[10:17], v[42:49], v[214:217]
	s_setprio 0
	s_barrier
	s_mov_b32 m0, s31
	s_add_i32 s33, s86, 0x80
	ds_read_b128 v[142:145], v141
	ds_read_b128 v[146:149], v141 offset:1024
	ds_read_b128 v[150:153], v141 offset:2048
	ds_read_b128 v[154:157], v141 offset:3072
	buffer_load_dwordx4 v134, s[8:11], s33 offen lds
	s_add_i32 s33, s86, 0x20080
	s_mov_b32 m0, s34
	s_nop 0
	buffer_load_dwordx4 v134, s[8:11], s33 offen lds
	s_waitcnt vmcnt(10)
	s_barrier
	s_waitcnt lgkmcnt(0)
	s_setprio 1
	s_waitcnt lgkmcnt(2)
	v_mfma_f32_16x16x128_f8f6f4 v[118:121], v[142:149], v[18:25], v[118:121]
	s_waitcnt lgkmcnt(0)
	v_mfma_f32_16x16x128_f8f6f4 v[110:113], v[150:157], v[18:25], v[110:113]
	v_mfma_f32_16x16x128_f8f6f4 v[102:105], v[142:149], v[26:33], v[102:105]
	v_mfma_f32_16x16x128_f8f6f4 v[94:97], v[150:157], v[26:33], v[158:161]
	v_mfma_f32_16x16x128_f8f6f4 v[86:89], v[142:149], v[34:41], v[162:165]
	v_mfma_f32_16x16x128_f8f6f4 v[78:81], v[150:157], v[34:41], v[166:169]
	v_mfma_f32_16x16x128_f8f6f4 v[70:73], v[142:149], v[42:49], v[170:173]
	v_mfma_f32_16x16x128_f8f6f4 v[18:21], v[150:157], v[42:49], v[174:177]
	s_setprio 0
	s_mov_b32 m0, s35
	s_barrier
	ds_read_b128 v[158:161], v138 offset:49152
	ds_read_b128 v[162:165], v138 offset:50176
	ds_read_b128 v[166:169], v138 offset:51200
	ds_read_b128 v[170:173], v138 offset:52224
	ds_read_b128 v[174:177], v138 offset:53248
	ds_read_b128 v[178:181], v138 offset:54272
	ds_read_b128 v[182:185], v138 offset:55296
	ds_read_b128 v[186:189], v138 offset:56320
	buffer_load_dwordx4 v1, s[44:47], s88 offen lds
	s_add_i32 s87, s87, 0x10800
	s_mov_b32 m0, s36
	s_nop 0
	buffer_load_dwordx4 v1, s[44:47], s87 offen lds
	s_barrier
	s_waitcnt lgkmcnt(0)
	s_setprio 1
	s_waitcnt lgkmcnt(6)
	v_mfma_f32_16x16x128_f8f6f4 v[62:65], v[2:9], v[158:165], v[62:65]
	v_mfma_f32_16x16x128_f8f6f4 v[58:61], v[10:17], v[158:165], v[58:61]
	s_waitcnt lgkmcnt(4)
	v_mfma_f32_16x16x128_f8f6f4 v[50:53], v[2:9], v[166:173], v[50:53]
	v_mfma_f32_16x16x128_f8f6f4 v[42:45], v[10:17], v[166:173], v[218:221]
	s_waitcnt lgkmcnt(2)
	v_mfma_f32_16x16x128_f8f6f4 v[34:37], v[2:9], v[174:181], v[222:225]
	v_mfma_f32_16x16x128_f8f6f4 v[26:29], v[10:17], v[174:181], v[226:229]
	s_waitcnt lgkmcnt(0)
	v_mfma_f32_16x16x128_f8f6f4 v[230:233], v[2:9], v[182:189], v[230:233]
	v_mfma_f32_16x16x128_f8f6f4 v[10:13], v[10:17], v[182:189], v[234:237]
	s_setprio 0
	s_barrier
	s_mov_b32 m0, s37
	s_add_i32 s33, s86, 0x2080
	buffer_load_dwordx4 v134, s[8:11], s33 offen lds
	s_add_i32 s86, s86, 0x22080
	s_mov_b32 m0, s38
	s_nop 0
	buffer_load_dwordx4 v134, s[8:11], s86 offen lds
	s_waitcnt vmcnt(6)
	s_barrier
	s_setprio 1
	v_mfma_f32_16x16x128_f8f6f4 v[54:57], v[142:149], v[158:165], v[54:57]
	v_mfma_f32_16x16x128_f8f6f4 v[46:49], v[150:157], v[158:165], v[238:241]
	v_mfma_f32_16x16x128_f8f6f4 v[38:41], v[142:149], v[166:173], v[242:245]
	v_mfma_f32_16x16x128_f8f6f4 v[30:33], v[150:157], v[166:173], v[246:249]
	v_mfma_f32_16x16x128_f8f6f4 v[22:25], v[142:149], v[174:181], v[250:253]
	v_mfma_f32_16x16x128_f8f6f4 v[14:17], v[150:157], v[174:181], v[130:133]
	v_mfma_f32_16x16x128_f8f6f4 v[6:9], v[142:149], v[182:189], v[66:69]
	v_mfma_f32_16x16x128_f8f6f4 v[2:5], v[150:157], v[182:189], v[190:193]
	s_setprio 0
	s_add_i32 s85, s85, 2
	s_addk_i32 s7, 0x1000
	s_addk_i32 s84, 0x100
	s_cmp_gt_u32 s85, 5
	s_barrier
	.p2align 6

.LBB0_2061:
	s_mov_b64 s[10:11], -1
	s_and_b64 vcc, exec, s[6:7]
	s_cbranch_vccz .LBB0_2055
	s_ashr_i32 s58, s9, 7
	s_lshl_b32 s10, s9, 8
	s_lshl_b32 s7, s58, 12
	s_and_b32 s10, s10, 0xf00
	s_or_b32 s30, s7, s10
	s_bfe_u32 s6, s9, 0x10006
	s_ashr_i32 s31, s30, 31
	s_mul_i32 s10, s30, 0xc00
	s_mul_hi_i32 s7, s30, 0xc00
	s_add_u32 s10, s82, s10
	s_addc_u32 s7, s83, s7
	s_lshl_b32 s9, s9, 3
	s_lshl_b32 s11, s6, 9
	s_and_b32 s9, s9, 0x180
	s_or_b32 s50, s11, s9
	s_lshl_b32 s9, s50, 1
	s_add_u32 s10, s10, s9
	s_addc_u32 s11, s7, 0
	s_mul_hi_i32 s57, s58, 0x220000
	s_mul_i32 s58, s58, 0x220000
	s_add_u32 s7, s44, s58
	s_addc_u32 s9, s71, s57
	s_lshl_b32 s59, s6, 8
	s_add_u32 s6, s7, s59
	s_addc_u32 s7, s9, 0
	s_add_u32 s9, s24, s58
	s_addc_u32 s12, s25, s57
	s_add_u32 s34, s9, s59
	s_addc_u32 s35, s12, 0
	global_load_dwordx4 v[2:5], v199, s[34:35]
	global_load_dwordx4 v[6:9], v200, s[34:35]
	global_load_dwordx4 v[10:13], v199, s[6:7]
	global_load_dwordx4 v[14:17], v200, s[6:7]
	v_mov_b32_e32 v193, v179
	v_lshl_add_u64 v[18:19], s[10:11], 0, v[192:193]
	v_mov_b32_e32 v195, v179
	v_lshl_add_u64 v[18:19], v[18:19], 0, v[194:195]
	global_load_dwordx4 v[126:129], v[18:19], off
	global_load_dwordx4 v[122:125], v[18:19], off offset:32
	global_load_dwordx4 v[118:121], v[18:19], off offset:64
	global_load_dwordx4 v[114:117], v[18:19], off offset:96
	global_load_dwordx4 v[110:113], v[18:19], off offset:128
	global_load_dwordx4 v[106:109], v[18:19], off offset:160
	global_load_dwordx4 v[102:105], v[18:19], off offset:192
	global_load_dwordx4 v[98:101], v[18:19], off offset:224
	s_waitcnt vmcnt(0)
	s_mov_b32 s9, s8
	s_mov_b32 s10, s8
	s_mov_b32 s11, s8
	s_mov_b32 s12, s8
	s_mov_b32 s13, s8
	s_mov_b32 s14, s8
	s_mov_b32 s15, s8
	s_mov_b32 s16, s8
	s_mov_b32 s17, s8
	s_mov_b32 s18, s8
	s_mov_b32 s19, s8
	s_mov_b32 s20, s8
	s_mov_b32 s21, s8
	s_mov_b32 s22, s8
	s_mov_b32 s23, s8
	s_mov_b32 s51, 1
	v_mov_b32_e32 v191, 0
	s_waitcnt vmcnt(11)
	ds_write_b128 v201, v[2:5]
	s_waitcnt vmcnt(10)
	ds_write_b128 v202, v[6:9]
	s_waitcnt vmcnt(9)
	ds_write_b128 v203, v[10:13] offset:32768
	s_waitcnt vmcnt(8)
	ds_write_b128 v204, v[14:17] offset:32768
	s_waitcnt lgkmcnt(0)
	s_barrier
	ds_read_b128 v[2:5], v205 offset:32768
	ds_read_b128 v[6:9], v205 offset:40960
	s_waitcnt vmcnt(7) lgkmcnt(1)
	v_mfma_f32_32x32x16_bf16 v[18:33], v[2:5], v[126:129], 0
	s_waitcnt lgkmcnt(0)
	v_mfma_f32_32x32x16_bf16 v[34:49], v[6:9], v[126:129], 0
	ds_read_b128 v[2:5], v206 offset:32768
	ds_read_b128 v[6:9], v206 offset:40960
	s_waitcnt vmcnt(6) lgkmcnt(1)
	v_mfma_f32_32x32x16_bf16 v[18:33], v[2:5], v[122:125], v[18:33]
	s_waitcnt lgkmcnt(0)
	v_mfma_f32_32x32x16_bf16 v[34:49], v[6:9], v[122:125], v[34:49]
	ds_read_b128 v[2:5], v207 offset:32768
	ds_read_b128 v[6:9], v207 offset:40960
	s_waitcnt vmcnt(5) lgkmcnt(1)
	v_mfma_f32_32x32x16_bf16 v[18:33], v[2:5], v[118:121], v[18:33]
	s_waitcnt lgkmcnt(0)
	v_mfma_f32_32x32x16_bf16 v[34:49], v[6:9], v[118:121], v[34:49]
	ds_read_b128 v[2:5], v208 offset:32768
	ds_read_b128 v[6:9], v208 offset:40960
	s_waitcnt vmcnt(4) lgkmcnt(1)
	v_mfma_f32_32x32x16_bf16 v[18:33], v[2:5], v[114:117], v[18:33]
	s_waitcnt lgkmcnt(0)
	v_mfma_f32_32x32x16_bf16 v[34:49], v[6:9], v[114:117], v[34:49]
	ds_read_b128 v[2:5], v209 offset:32768
	ds_read_b128 v[6:9], v209 offset:40960
	s_waitcnt vmcnt(3) lgkmcnt(1)
	v_mfma_f32_32x32x16_bf16 v[18:33], v[2:5], v[110:113], v[18:33]
	s_waitcnt lgkmcnt(0)
	v_mfma_f32_32x32x16_bf16 v[34:49], v[6:9], v[110:113], v[34:49]
	ds_read_b128 v[2:5], v210 offset:32768
	ds_read_b128 v[6:9], v210 offset:40960
	global_load_dwordx4 v[50:53], v215, s[34:35]
	global_load_dwordx4 v[54:57], v214, s[34:35]
	global_load_dwordx4 v[58:61], v214, s[6:7]
	global_load_dwordx4 v[62:65], v215, s[6:7]
	ds_read_b128 v[66:69], v212 offset:40960
	s_waitcnt vmcnt(6) lgkmcnt(2)
	v_mfma_f32_32x32x16_bf16 v[18:33], v[2:5], v[106:109], v[18:33]
	ds_read_b128 v[2:5], v211 offset:32768
	s_waitcnt lgkmcnt(2)
	v_mfma_f32_32x32x16_bf16 v[34:49], v[6:9], v[106:109], v[34:49]
	ds_read_b128 v[6:9], v211 offset:40960
	s_waitcnt vmcnt(5) lgkmcnt(1)
	v_mfma_f32_32x32x16_bf16 v[18:33], v[2:5], v[102:105], v[18:33]
	ds_read_b128 v[2:5], v212 offset:32768
	global_load_dwordx4 v[130:133], v216, s[34:35]
	global_load_dwordx4 v[138:141], v216, s[6:7]
	global_load_dwordx4 v[134:137], v217, s[34:35]
	global_load_dwordx4 v[142:145], v217, s[6:7]
	s_waitcnt vmcnt(4)
	s_waitcnt vmcnt(6)
	ds_write_b128 v201, v[54:57] offset:16384
	ds_write_b128 v202, v[50:53] offset:16384
	s_waitcnt vmcnt(5)
	ds_write_b128 v203, v[58:61] offset:49152
	s_waitcnt vmcnt(4)
	ds_write_b128 v204, v[62:65] offset:49152
	s_waitcnt lgkmcnt(5)
	v_mfma_f32_32x32x16_bf16 v[34:49], v[6:9], v[102:105], v[34:49]
	s_waitcnt lgkmcnt(0)
	s_barrier
	v_mfma_f32_32x32x16_bf16 v[18:33], v[2:5], v[98:101], v[18:33]
	v_mov_b64_e32 v[2:3], s[8:9]
	v_mov_b64_e32 v[16:17], s[22:23]
	v_mov_b64_e32 v[4:5], s[10:11]
	v_mov_b64_e32 v[6:7], s[12:13]
	v_mov_b64_e32 v[8:9], s[14:15]
	v_mov_b64_e32 v[10:11], s[16:17]
	v_mov_b64_e32 v[12:13], s[18:19]
	v_mfma_f32_32x32x16_bf16 v[34:49], v[66:69], v[98:101], v[34:49]
	s_nop 3
	v_max_f32_e32 v66, v19, v19
	v_max_f32_e32 v67, v18, v18
	v_max_f32_e32 v66, v67, v66
	v_max3_f32 v66, v66, v20, v21
	v_max3_f32 v66, v66, v22, v23
	v_max3_f32 v66, v66, v24, v25
	v_max3_f32 v66, v66, v26, v27
	v_max3_f32 v66, v66, v28, v29
	v_max3_f32 v66, v66, v30, v31
	v_max3_f32 v50, v66, v32, v33
	v_max3_f32 v50, v50, v34, v35
	v_max3_f32 v50, v50, v36, v37
	v_max3_f32 v50, v50, v38, v39
	v_max3_f32 v50, v50, v40, v41
	v_max3_f32 v50, v50, v42, v43
	v_max3_f32 v50, v50, v44, v45
	v_max3_f32 v50, v50, v46, v47
	v_max3_f32 v50, v50, v48, v49
	v_mov_b32_e32 v51, v50
	s_nop 1
	v_permlane32_swap_b32_e32 v50, v51
	v_max_f32_e32 v51, v51, v51
	v_max_f32_e32 v50, v50, v50
	v_max_f32_e32 v50, v50, v51
	v_add_f32_e32 v51, 0x7149f2ca, v50
	v_cmp_ge_f32_e32 vcc, s37, v51
	s_cmp_eq_u64 vcc, exec
	v_max_f32_e32 v50, 0xf149f2ca, v50
	s_cselect_b64 vcc, -1, 0
	v_sub_f32_e32 v51, 0xf149f2ca, v50
	v_cndmask_b32_e32 v166, v50, v213, vcc
	v_mul_f32_e32 v51, 0x3e0293ee, v51
	v_mul_f32_e32 v50, 0xbe0293ee, v166
	v_exp_f32_e32 v51, v51
	v_mov_b32_e32 v52, v50
	v_fmamk_f32 v18, v18, 0x3e0293ee, v50
	v_fmamk_f32 v19, v19, 0x3e0293ee, v50
	v_fmamk_f32 v20, v20, 0x3e0293ee, v50
	v_fmamk_f32 v21, v21, 0x3e0293ee, v50
	v_fmamk_f32 v22, v22, 0x3e0293ee, v50
	v_fmamk_f32 v23, v23, 0x3e0293ee, v50
	v_fmamk_f32 v24, v24, 0x3e0293ee, v50
	v_fmamk_f32 v25, v25, 0x3e0293ee, v50
	v_fmamk_f32 v26, v26, 0x3e0293ee, v50
	v_fmamk_f32 v27, v27, 0x3e0293ee, v50
	v_fmamk_f32 v28, v28, 0x3e0293ee, v50
	v_fmamk_f32 v29, v29, 0x3e0293ee, v50
	v_fmamk_f32 v30, v30, 0x3e0293ee, v50
	v_fmamk_f32 v31, v31, 0x3e0293ee, v50
	v_fmamk_f32 v32, v32, 0x3e0293ee, v50
	v_fmac_f32_e32 v52, 0x3e0293ee, v33
	v_exp_f32_e32 v177, v18
	v_exp_f32_e32 v223, v19
	v_exp_f32_e32 v163, v20
	v_exp_f32_e32 v220, v21
	v_exp_f32_e32 v164, v22
	v_exp_f32_e32 v176, v23
	v_exp_f32_e32 v165, v24
	v_exp_f32_e32 v175, v25
	v_exp_f32_e32 v172, v26
	v_exp_f32_e32 v174, v27
	v_exp_f32_e32 v171, v28
	v_exp_f32_e32 v173, v29
	v_exp_f32_e32 v168, v30
	v_exp_f32_e32 v170, v31
	v_exp_f32_e32 v167, v32
	v_exp_f32_e32 v169, v52
	s_or_b32 s6, s58, s59
	v_mov_b64_e32 v[14:15], s[20:21]
	s_add_u32 s10, s52, s6
	v_pk_fma_f32 v[152:153], v[48:49], s[28:29], v[50:51] op_sel_hi:[1,0,0]
	v_pk_fma_f32 v[158:159], v[46:47], s[28:29], v[50:51] op_sel_hi:[1,0,0]
	v_pk_fma_f32 v[160:161], v[44:45], s[28:29], v[50:51] op_sel_hi:[1,0,0]
	v_pk_fma_f32 v[146:147], v[42:43], s[28:29], v[50:51] op_sel_hi:[1,0,0]
	v_pk_fma_f32 v[148:149], v[40:41], s[28:29], v[50:51] op_sel_hi:[1,0,0]
	v_pk_fma_f32 v[150:151], v[38:39], s[28:29], v[50:51] op_sel_hi:[1,0,0]
	v_pk_fma_f32 v[154:155], v[36:37], s[28:29], v[50:51] op_sel_hi:[1,0,0]
	v_pk_fma_f32 v[156:157], v[34:35], s[28:29], v[50:51] op_sel_hi:[1,0,0]
	v_cndmask_b32_e64 v193, v51, 1.0, vcc
	v_mov_b64_e32 v[64:65], v[16:17]
	v_mov_b64_e32 v[48:49], v[16:17]
	v_mov_b64_e32 v[32:33], v[16:17]
	s_addc_u32 s11, s53, s57
	v_mov_b64_e32 v[62:63], v[14:15]
	v_mov_b64_e32 v[60:61], v[12:13]
	v_mov_b64_e32 v[58:59], v[10:11]
	v_mov_b64_e32 v[56:57], v[8:9]
	v_mov_b64_e32 v[54:55], v[6:7]
	v_mov_b64_e32 v[52:53], v[4:5]
	v_mov_b64_e32 v[50:51], v[2:3]
	v_mov_b64_e32 v[46:47], v[14:15]
	v_mov_b64_e32 v[44:45], v[12:13]
	v_mov_b64_e32 v[42:43], v[10:11]
	v_mov_b64_e32 v[40:41], v[8:9]
	v_mov_b64_e32 v[38:39], v[6:7]
	v_mov_b64_e32 v[36:37], v[4:5]
	v_mov_b64_e32 v[34:35], v[2:3]
	v_mov_b64_e32 v[30:31], v[14:15]
	v_mov_b64_e32 v[28:29], v[12:13]
	v_mov_b64_e32 v[26:27], v[10:11]
	v_mov_b64_e32 v[24:25], v[8:9]
	v_mov_b64_e32 v[22:23], v[6:7]
	v_mov_b64_e32 v[20:21], v[4:5]
	v_mov_b64_e32 v[18:19], v[2:3]
	.p2align 6

.Lfw_10_b_p:
	s_barrier
	s_setprio 1
	v_mfma_f32_16x16x32_bf16 v[54:57], v[178:181], v[146:149], 0
	v_mfma_f32_16x16x32_bf16 v[50:53], v[200:203], v[146:149], 0
	v_mfma_f32_16x16x32_bf16 v[38:41], v[178:181], v[154:157], 0
	v_mfma_f32_16x16x32_bf16 v[34:37], v[200:203], v[154:157], 0
	v_mfma_f32_16x16x32_bf16 v[22:25], v[178:181], v[162:165], 0
	v_mfma_f32_16x16x32_bf16 v[18:21], v[200:203], v[162:165], 0
	v_mfma_f32_16x16x32_bf16 v[6:9], v[178:181], v[170:173], 0
	v_mfma_f32_16x16x32_bf16 v[2:5], v[200:203], v[170:173], 0
	v_mfma_f32_16x16x32_bf16 v[54:57], v[182:185], v[150:153], v[54:57]
	v_mfma_f32_16x16x32_bf16 v[50:53], v[204:207], v[150:153], v[50:53]
	v_mfma_f32_16x16x32_bf16 v[38:41], v[182:185], v[158:161], v[38:41]
	v_mfma_f32_16x16x32_bf16 v[34:37], v[204:207], v[158:161], v[34:37]
	v_mfma_f32_16x16x32_bf16 v[22:25], v[182:185], v[166:169], v[22:25]
	v_mfma_f32_16x16x32_bf16 v[18:21], v[204:207], v[166:169], v[18:21]
	v_mfma_f32_16x16x32_bf16 v[6:9], v[182:185], v[174:177], v[6:9]
	v_mfma_f32_16x16x32_bf16 v[2:5], v[204:207], v[174:177], v[2:5]
	s_setprio 0
	s_barrier
	ds_read_b128 v[130:133], v198
	ds_read_b128 v[134:137], v198 offset:1024
	ds_read_b128 v[138:141], v198 offset:2048
	ds_read_b128 v[142:145], v198 offset:3072
	s_mov_b32 m0, s21
	s_add_i32 s33, s78, 0x40000
	ds_read_b128 v[146:149], v196 offset:32768
	ds_read_b128 v[150:153], v196 offset:33792
	ds_read_b128 v[154:157], v196 offset:34816
	ds_read_b128 v[158:161], v196 offset:35840
	ds_read_b128 v[162:165], v196 offset:36864
	ds_read_b128 v[166:169], v196 offset:37888
	ds_read_b128 v[170:173], v196 offset:38912
	ds_read_b128 v[174:177], v196 offset:39936
	buffer_load_dwordx4 v1, s[48:51], s33 offen lds
	s_add_i32 s33, s78, 0x60000
	s_mov_b32 m0, s22
	s_nop 0
	buffer_load_dwordx4 v1, s[48:51], s33 offen lds
	s_waitcnt lgkmcnt(8)
	s_barrier
	s_waitcnt lgkmcnt(0)
	s_setprio 1
	s_waitcnt lgkmcnt(7)
	v_mfma_f32_16x16x32_bf16 v[126:129], v[130:133], v[146:149], v[126:129]
	v_mfma_f32_16x16x32_bf16 v[122:125], v[138:141], v[146:149], v[122:125]
	s_waitcnt lgkmcnt(5)
	v_mfma_f32_16x16x32_bf16 v[110:113], v[130:133], v[154:157], v[110:113]
	v_mfma_f32_16x16x32_bf16 v[106:109], v[138:141], v[154:157], v[106:109]
	s_waitcnt lgkmcnt(3)
	v_mfma_f32_16x16x32_bf16 v[94:97], v[130:133], v[162:165], v[94:97]
	v_mfma_f32_16x16x32_bf16 v[90:93], v[138:141], v[162:165], v[90:93]
	s_waitcnt lgkmcnt(1)
	v_mfma_f32_16x16x32_bf16 v[78:81], v[130:133], v[170:173], v[78:81]
	v_mfma_f32_16x16x32_bf16 v[74:77], v[138:141], v[170:173], v[74:77]
	v_mfma_f32_16x16x32_bf16 v[126:129], v[134:137], v[150:153], v[126:129]
	v_mfma_f32_16x16x32_bf16 v[122:125], v[142:145], v[150:153], v[122:125]
	v_mfma_f32_16x16x32_bf16 v[110:113], v[134:137], v[158:161], v[110:113]
	v_mfma_f32_16x16x32_bf16 v[106:109], v[142:145], v[158:161], v[106:109]
	v_mfma_f32_16x16x32_bf16 v[94:97], v[134:137], v[166:169], v[94:97]
	v_mfma_f32_16x16x32_bf16 v[90:93], v[142:145], v[166:169], v[90:93]
	s_waitcnt lgkmcnt(0)
	v_mfma_f32_16x16x32_bf16 v[78:81], v[134:137], v[174:177], v[78:81]
	v_mfma_f32_16x16x32_bf16 v[74:77], v[142:145], v[174:177], v[74:77]
	s_setprio 0
	s_barrier
	s_mov_b32 m0, s28
	s_add_i32 s33, s73, 0x80
	ds_read_b128 v[178:181], v199
	ds_read_b128 v[182:185], v199 offset:1024
	ds_read_b128 v[200:203], v199 offset:2048
	ds_read_b128 v[204:207], v199 offset:3072
	buffer_load_dwordx4 v192, s[8:11], s33 offen lds
	s_add_i32 s33, s73, 0x20080
	s_mov_b32 m0, s29
	s_nop 0
	buffer_load_dwordx4 v192, s[8:11], s33 offen lds
	s_waitcnt vmcnt(10)
	s_barrier
	s_waitcnt lgkmcnt(0)
	s_setprio 1
	s_waitcnt lgkmcnt(3)
	v_mfma_f32_16x16x32_bf16 v[118:121], v[178:181], v[146:149], v[118:121]
	s_waitcnt lgkmcnt(1)
	v_mfma_f32_16x16x32_bf16 v[114:117], v[200:203], v[146:149], v[114:117]
	v_mfma_f32_16x16x32_bf16 v[102:105], v[178:181], v[154:157], v[102:105]
	v_mfma_f32_16x16x32_bf16 v[98:101], v[200:203], v[154:157], v[98:101]
	v_mfma_f32_16x16x32_bf16 v[86:89], v[178:181], v[162:165], v[86:89]
	v_mfma_f32_16x16x32_bf16 v[82:85], v[200:203], v[162:165], v[82:85]
	v_mfma_f32_16x16x32_bf16 v[70:73], v[178:181], v[170:173], v[70:73]
	v_mfma_f32_16x16x32_bf16 v[66:69], v[200:203], v[170:173], v[66:69]
	v_mfma_f32_16x16x32_bf16 v[118:121], v[182:185], v[150:153], v[118:121]
	s_waitcnt lgkmcnt(0)
	v_mfma_f32_16x16x32_bf16 v[114:117], v[204:207], v[150:153], v[114:117]
	v_mfma_f32_16x16x32_bf16 v[102:105], v[182:185], v[158:161], v[102:105]
	v_mfma_f32_16x16x32_bf16 v[98:101], v[204:207], v[158:161], v[98:101]
	v_mfma_f32_16x16x32_bf16 v[86:89], v[182:185], v[166:169], v[86:89]
	v_mfma_f32_16x16x32_bf16 v[82:85], v[204:207], v[166:169], v[82:85]
	v_mfma_f32_16x16x32_bf16 v[70:73], v[182:185], v[174:177], v[70:73]
	v_mfma_f32_16x16x32_bf16 v[66:69], v[204:207], v[174:177], v[66:69]
	s_setprio 0
	s_mov_b32 m0, s30
	s_barrier
	ds_read_b128 v[146:149], v196 offset:49152
	ds_read_b128 v[150:153], v196 offset:50176
	ds_read_b128 v[154:157], v196 offset:51200
	ds_read_b128 v[158:161], v196 offset:52224
	ds_read_b128 v[162:165], v196 offset:53248
	ds_read_b128 v[166:169], v196 offset:54272
	ds_read_b128 v[170:173], v196 offset:55296
	ds_read_b128 v[174:177], v196 offset:56320
	buffer_load_dwordx4 v1, s[48:51], s79 offen lds
	s_add_i32 s78, s78, 0x20080
	s_mov_b32 m0, s31
	s_nop 0
	buffer_load_dwordx4 v1, s[48:51], s78 offen lds
	s_barrier
	s_waitcnt lgkmcnt(0)
	s_setprio 1
	s_waitcnt lgkmcnt(7)
	v_mfma_f32_16x16x32_bf16 v[62:65], v[130:133], v[146:149], v[62:65]
	v_mfma_f32_16x16x32_bf16 v[58:61], v[138:141], v[146:149], v[58:61]
	s_waitcnt lgkmcnt(5)
	v_mfma_f32_16x16x32_bf16 v[46:49], v[130:133], v[154:157], v[46:49]
	v_mfma_f32_16x16x32_bf16 v[42:45], v[138:141], v[154:157], v[42:45]
	s_waitcnt lgkmcnt(3)
	v_mfma_f32_16x16x32_bf16 v[30:33], v[130:133], v[162:165], v[30:33]
	v_mfma_f32_16x16x32_bf16 v[26:29], v[138:141], v[162:165], v[26:29]
	s_waitcnt lgkmcnt(1)
	v_mfma_f32_16x16x32_bf16 v[14:17], v[130:133], v[170:173], v[14:17]
	v_mfma_f32_16x16x32_bf16 v[10:13], v[138:141], v[170:173], v[10:13]
	v_mfma_f32_16x16x32_bf16 v[62:65], v[134:137], v[150:153], v[62:65]
	v_mfma_f32_16x16x32_bf16 v[58:61], v[142:145], v[150:153], v[58:61]
	v_mfma_f32_16x16x32_bf16 v[46:49], v[134:137], v[158:161], v[46:49]
	v_mfma_f32_16x16x32_bf16 v[42:45], v[142:145], v[158:161], v[42:45]
	v_mfma_f32_16x16x32_bf16 v[30:33], v[134:137], v[166:169], v[30:33]
	v_mfma_f32_16x16x32_bf16 v[26:29], v[142:145], v[166:169], v[26:29]
	s_waitcnt lgkmcnt(0)
	v_mfma_f32_16x16x32_bf16 v[14:17], v[134:137], v[174:177], v[14:17]
	v_mfma_f32_16x16x32_bf16 v[10:13], v[142:145], v[174:177], v[10:13]
	s_setprio 0
	s_barrier
	s_mov_b32 m0, s34
	s_add_i32 s33, s73, 0x40080
	buffer_load_dwordx4 v192, s[8:11], s33 offen lds
	s_add_i32 s73, s73, 0x60080
	s_mov_b32 m0, s35
	s_nop 0
	buffer_load_dwordx4 v192, s[8:11], s73 offen lds
	s_waitcnt vmcnt(6)
	s_barrier
	s_setprio 1
	v_mfma_f32_16x16x32_bf16 v[54:57], v[178:181], v[146:149], v[54:57]
	v_mfma_f32_16x16x32_bf16 v[50:53], v[200:203], v[146:149], v[50:53]
	v_mfma_f32_16x16x32_bf16 v[38:41], v[178:181], v[154:157], v[38:41]
	v_mfma_f32_16x16x32_bf16 v[34:37], v[200:203], v[154:157], v[34:37]
	v_mfma_f32_16x16x32_bf16 v[22:25], v[178:181], v[162:165], v[22:25]
	v_mfma_f32_16x16x32_bf16 v[18:21], v[200:203], v[162:165], v[18:21]
	v_mfma_f32_16x16x32_bf16 v[6:9], v[178:181], v[170:173], v[6:9]
	v_mfma_f32_16x16x32_bf16 v[2:5], v[200:203], v[170:173], v[2:5]
	v_mfma_f32_16x16x32_bf16 v[54:57], v[182:185], v[150:153], v[54:57]
	v_mfma_f32_16x16x32_bf16 v[50:53], v[204:207], v[150:153], v[50:53]
	v_mfma_f32_16x16x32_bf16 v[38:41], v[182:185], v[158:161], v[38:41]
	v_mfma_f32_16x16x32_bf16 v[34:37], v[204:207], v[158:161], v[34:37]
	v_mfma_f32_16x16x32_bf16 v[22:25], v[182:185], v[166:169], v[22:25]
	v_mfma_f32_16x16x32_bf16 v[18:21], v[204:207], v[166:169], v[18:21]
	v_mfma_f32_16x16x32_bf16 v[6:9], v[182:185], v[174:177], v[6:9]
	v_mfma_f32_16x16x32_bf16 v[2:5], v[204:207], v[174:177], v[2:5]
	s_setprio 0
	s_add_i32 s13, s13, 2
	s_addk_i32 s7, 0x100
	s_addk_i32 s12, 0x100
	s_cmp_gt_u32 s13, 13
	s_barrier
	.p2align 6

.Lfw_11_b:
	s_barrier
	s_setprio 1
	v_mfma_f32_16x16x128_f8f6f4 v[106:109], v[198:205], v[18:25], v[106:109]
	v_mfma_f32_16x16x128_f8f6f4 v[98:101], v[206:213], v[18:25], v[98:101]
	v_mfma_f32_16x16x128_f8f6f4 v[90:93], v[198:205], v[26:33], v[90:93]
	v_mfma_f32_16x16x128_f8f6f4 v[82:85], v[206:213], v[26:33], v[82:85]
	v_mfma_f32_16x16x128_f8f6f4 v[74:77], v[198:205], v[34:41], v[74:77]
	v_mfma_f32_16x16x128_f8f6f4 v[66:69], v[206:213], v[34:41], v[66:69]
	v_mfma_f32_16x16x128_f8f6f4 v[58:61], v[198:205], v[42:49], v[58:61]
	v_mfma_f32_16x16x128_f8f6f4 v[50:53], v[206:213], v[42:49], v[50:53]
	s_setprio 0
	v_add_u32_e32 v14, 0x18000, v189
	s_barrier
	ds_read_b128 v[2:5], v14
	ds_read_b128 v[6:9], v14 offset:1024
	ds_read_b128 v[10:13], v14 offset:2048
	ds_read_b128 v[14:17], v14 offset:3072
	s_mov_b32 m0, s22
	ds_read_b128 v[18:21], v191 offset:32768
	ds_read_b128 v[22:25], v191 offset:33792
	ds_read_b128 v[26:29], v191 offset:34816
	ds_read_b128 v[30:33], v191 offset:35840
	ds_read_b128 v[34:37], v191 offset:36864
	ds_read_b128 v[38:41], v191 offset:37888
	ds_read_b128 v[42:45], v191 offset:38912
	ds_read_b128 v[46:49], v191 offset:39936
	buffer_load_dwordx4 v196, s[40:43], s58 offen lds
	s_mov_b32 m0, s23
	s_nop 0
	buffer_load_dwordx4 v197, s[40:43], s58 offen lds
	s_waitcnt lgkmcnt(8)
	s_barrier
	s_waitcnt lgkmcnt(0)
	s_setprio 1
	s_waitcnt lgkmcnt(6)
	v_mfma_f32_16x16x128_f8f6f4 v[174:177], v[2:9], v[18:25], v[174:177]
	v_mfma_f32_16x16x128_f8f6f4 v[166:169], v[10:17], v[18:25], v[166:169]
	s_waitcnt lgkmcnt(4)
	v_mfma_f32_16x16x128_f8f6f4 v[158:161], v[2:9], v[26:33], v[158:161]
	v_mfma_f32_16x16x128_f8f6f4 v[150:153], v[10:17], v[26:33], v[150:153]
	s_waitcnt lgkmcnt(2)
	v_mfma_f32_16x16x128_f8f6f4 v[142:145], v[2:9], v[34:41], v[142:145]
	v_mfma_f32_16x16x128_f8f6f4 v[134:137], v[10:17], v[34:41], v[134:137]
	s_waitcnt lgkmcnt(0)
	v_mfma_f32_16x16x128_f8f6f4 v[126:129], v[2:9], v[42:49], v[126:129]
	v_mfma_f32_16x16x128_f8f6f4 v[118:121], v[10:17], v[42:49], v[118:121]
	s_setprio 0
	s_barrier
	s_mov_b32 m0, s25
	v_add_u32_e32 v208, 0x1c000, v189
	ds_read_b128 v[196:199], v208
	ds_read_b128 v[200:203], v208 offset:1024
	ds_read_b128 v[204:207], v208 offset:2048
	ds_read_b128 v[208:211], v208 offset:3072
	buffer_load_dwordx4 v184, s[12:15], s7 offen lds
	s_add_i32 s7, s6, 0x10080
	s_mov_b32 m0, s26
	s_nop 0
	buffer_load_dwordx4 v184, s[12:15], s7 offen lds
	s_waitcnt vmcnt(10)
	s_barrier
	s_waitcnt lgkmcnt(0)
	s_setprio 1
	s_waitcnt lgkmcnt(2)
	v_mfma_f32_16x16x128_f8f6f4 v[170:173], v[196:203], v[18:25], v[170:173]
	s_waitcnt lgkmcnt(0)
	v_mfma_f32_16x16x128_f8f6f4 v[162:165], v[204:211], v[18:25], v[162:165]
	v_mfma_f32_16x16x128_f8f6f4 v[154:157], v[196:203], v[26:33], v[154:157]
	v_mfma_f32_16x16x128_f8f6f4 v[146:149], v[204:211], v[26:33], v[146:149]
	v_mfma_f32_16x16x128_f8f6f4 v[138:141], v[196:203], v[34:41], v[138:141]
	v_mfma_f32_16x16x128_f8f6f4 v[130:133], v[204:211], v[34:41], v[130:133]
	v_mfma_f32_16x16x128_f8f6f4 v[122:125], v[196:203], v[42:49], v[122:125]
	v_mfma_f32_16x16x128_f8f6f4 v[114:117], v[204:211], v[42:49], v[114:117]
	s_setprio 0
	s_mov_b32 m0, s27
	s_barrier
	ds_read_b128 v[18:21], v191 offset:49152
	ds_read_b128 v[22:25], v191 offset:50176
	ds_read_b128 v[26:29], v191 offset:51200
	ds_read_b128 v[30:33], v191 offset:52224
	ds_read_b128 v[34:37], v191 offset:53248
	ds_read_b128 v[38:41], v191 offset:54272
	ds_read_b128 v[42:45], v191 offset:55296
	ds_read_b128 v[46:49], v191 offset:56320
	buffer_load_dwordx4 v214, s[40:43], s57 offen lds
	s_mov_b32 m0, s28
	s_nop 0
	buffer_load_dwordx4 v215, s[40:43], s57 offen lds
	s_barrier
	s_waitcnt lgkmcnt(0)
	s_setprio 1
	s_waitcnt lgkmcnt(6)
	v_mfma_f32_16x16x128_f8f6f4 v[110:113], v[2:9], v[18:25], v[110:113]
	v_mfma_f32_16x16x128_f8f6f4 v[102:105], v[10:17], v[18:25], v[102:105]
	s_waitcnt lgkmcnt(4)
	v_mfma_f32_16x16x128_f8f6f4 v[94:97], v[2:9], v[26:33], v[94:97]
	v_mfma_f32_16x16x128_f8f6f4 v[86:89], v[10:17], v[26:33], v[86:89]
	s_waitcnt lgkmcnt(2)
	v_mfma_f32_16x16x128_f8f6f4 v[78:81], v[2:9], v[34:41], v[78:81]
	v_mfma_f32_16x16x128_f8f6f4 v[70:73], v[10:17], v[34:41], v[70:73]
	s_waitcnt lgkmcnt(0)
	v_mfma_f32_16x16x128_f8f6f4 v[62:65], v[2:9], v[42:49], v[62:65]
	v_mfma_f32_16x16x128_f8f6f4 v[54:57], v[10:17], v[42:49], v[54:57]
	s_setprio 0
	s_barrier
	s_mov_b32 m0, s29
	s_add_i32 s7, s6, 0x20080
	buffer_load_dwordx4 v184, s[12:15], s7 offen lds
	s_add_i32 s6, s6, 0x30080
	s_mov_b32 m0, s30
	s_nop 0
	buffer_load_dwordx4 v184, s[12:15], s6 offen lds
	s_waitcnt vmcnt(6)
	s_barrier
	s_setprio 1
	v_mfma_f32_16x16x128_f8f6f4 v[106:109], v[196:203], v[18:25], v[106:109]
	v_mfma_f32_16x16x128_f8f6f4 v[98:101], v[204:211], v[18:25], v[98:101]
	v_mfma_f32_16x16x128_f8f6f4 v[90:93], v[196:203], v[26:33], v[90:93]
	v_mfma_f32_16x16x128_f8f6f4 v[82:85], v[204:211], v[26:33], v[82:85]
	v_mfma_f32_16x16x128_f8f6f4 v[74:77], v[196:203], v[34:41], v[74:77]
	v_mfma_f32_16x16x128_f8f6f4 v[66:69], v[204:211], v[34:41], v[66:69]
	v_mfma_f32_16x16x128_f8f6f4 v[58:61], v[196:203], v[42:49], v[58:61]
	v_mfma_f32_16x16x128_f8f6f4 v[50:53], v[204:211], v[42:49], v[50:53]
	s_setprio 0
	s_add_i32 s8, s8, 2
	s_addk_i32 s9, 0x100
	s_cmp_gt_u32 s8, 5
	s_barrier
	s_cbranch_scc1 .LBB0_2423
	.p2align 6

.Lfw_12_b_p:
	s_barrier
	s_setprio 1
	v_mfma_f32_16x16x128_f8f6f4 v[54:57], v[122:129], v[66:73], 0
	v_mfma_f32_16x16x128_f8f6f4 v[238:241], v[190:197], v[66:73], 0
	v_mfma_f32_16x16x128_f8f6f4 v[242:245], v[122:129], v[74:81], 0
	v_mfma_f32_16x16x128_f8f6f4 v[246:249], v[190:197], v[74:81], 0
	v_mfma_f32_16x16x128_f8f6f4 v[250:253], v[122:129], v[82:89], 0
	v_mfma_f32_16x16x128_f8f6f4 v[130:133], v[190:197], v[82:89], 0
	v_mfma_f32_16x16x128_f8f6f4 v[66:69], v[122:129], v[90:97], 0
	v_mfma_f32_16x16x128_f8f6f4 v[190:193], v[190:197], v[90:97], 0
	s_setprio 0
	s_barrier
	s_nop 4
	ds_read_b128 v[2:5], v140
	ds_read_b128 v[6:9], v140 offset:1024
	ds_read_b128 v[10:13], v140 offset:2048
	ds_read_b128 v[14:17], v140 offset:3072
	s_mov_b32 m0, s27
	s_add_i32 s33, s86, 0x20000
	ds_read_b128 v[18:21], v138 offset:32768
	ds_read_b128 v[22:25], v138 offset:33792
	ds_read_b128 v[26:29], v138 offset:34816
	ds_read_b128 v[30:33], v138 offset:35840
	ds_read_b128 v[34:37], v138 offset:36864
	ds_read_b128 v[38:41], v138 offset:37888
	ds_read_b128 v[42:45], v138 offset:38912
	ds_read_b128 v[46:49], v138 offset:39936
	buffer_load_dwordx4 v1, s[44:47], s33 offen lds
	s_add_i32 s33, s86, 0x30000
	s_mov_b32 m0, s28
	s_nop 0
	buffer_load_dwordx4 v1, s[44:47], s33 offen lds
	s_waitcnt lgkmcnt(8)
	s_barrier
	s_waitcnt lgkmcnt(0)
	s_setprio 1
	s_waitcnt lgkmcnt(6)
	v_mfma_f32_16x16x128_f8f6f4 v[126:129], v[2:9], v[18:25], v[198:201]
	v_mfma_f32_16x16x128_f8f6f4 v[122:125], v[10:17], v[18:25], v[202:205]
	s_waitcnt lgkmcnt(4)
	v_mfma_f32_16x16x128_f8f6f4 v[114:117], v[2:9], v[26:33], v[114:117]
	v_mfma_f32_16x16x128_f8f6f4 v[106:109], v[10:17], v[26:33], v[106:109]
	s_waitcnt lgkmcnt(2)
	v_mfma_f32_16x16x128_f8f6f4 v[98:101], v[2:9], v[34:41], v[98:101]
	v_mfma_f32_16x16x128_f8f6f4 v[90:93], v[10:17], v[34:41], v[206:209]
	s_waitcnt lgkmcnt(0)
	v_mfma_f32_16x16x128_f8f6f4 v[82:85], v[2:9], v[42:49], v[210:213]
	v_mfma_f32_16x16x128_f8f6f4 v[74:77], v[10:17], v[42:49], v[214:217]
	s_setprio 0
	s_barrier
	s_mov_b32 m0, s30
	s_add_i32 s33, s85, 0x80
	ds_read_b128 v[142:145], v141
	ds_read_b128 v[146:149], v141 offset:1024
	ds_read_b128 v[150:153], v141 offset:2048
	ds_read_b128 v[154:157], v141 offset:3072
	buffer_load_dwordx4 v134, s[8:11], s33 offen lds
	s_add_i32 s33, s85, 0x20080
	s_mov_b32 m0, s31
	s_nop 0
	buffer_load_dwordx4 v134, s[8:11], s33 offen lds
	s_waitcnt vmcnt(10)
	s_barrier
	s_waitcnt lgkmcnt(0)
	s_setprio 1
	s_waitcnt lgkmcnt(2)
	v_mfma_f32_16x16x128_f8f6f4 v[118:121], v[142:149], v[18:25], v[118:121]
	s_waitcnt lgkmcnt(0)
	v_mfma_f32_16x16x128_f8f6f4 v[110:113], v[150:157], v[18:25], v[110:113]
	v_mfma_f32_16x16x128_f8f6f4 v[102:105], v[142:149], v[26:33], v[102:105]
	v_mfma_f32_16x16x128_f8f6f4 v[94:97], v[150:157], v[26:33], v[158:161]
	v_mfma_f32_16x16x128_f8f6f4 v[86:89], v[142:149], v[34:41], v[162:165]
	v_mfma_f32_16x16x128_f8f6f4 v[78:81], v[150:157], v[34:41], v[166:169]
	v_mfma_f32_16x16x128_f8f6f4 v[70:73], v[142:149], v[42:49], v[170:173]
	v_mfma_f32_16x16x128_f8f6f4 v[18:21], v[150:157], v[42:49], v[174:177]
	s_setprio 0
	s_mov_b32 m0, s34
	s_barrier
	ds_read_b128 v[158:161], v138 offset:49152
	ds_read_b128 v[162:165], v138 offset:50176
	ds_read_b128 v[166:169], v138 offset:51200
	ds_read_b128 v[170:173], v138 offset:52224
	ds_read_b128 v[174:177], v138 offset:53248
	ds_read_b128 v[178:181], v138 offset:54272
	ds_read_b128 v[182:185], v138 offset:55296
	ds_read_b128 v[186:189], v138 offset:56320
	buffer_load_dwordx4 v1, s[44:47], s87 offen lds
	s_add_i32 s86, s86, 0x10800
	s_mov_b32 m0, s35
	s_nop 0
	buffer_load_dwordx4 v1, s[44:47], s86 offen lds
	s_barrier
	s_waitcnt lgkmcnt(0)
	s_setprio 1
	s_waitcnt lgkmcnt(6)
	v_mfma_f32_16x16x128_f8f6f4 v[62:65], v[2:9], v[158:165], v[62:65]
	v_mfma_f32_16x16x128_f8f6f4 v[58:61], v[10:17], v[158:165], v[58:61]
	s_waitcnt lgkmcnt(4)
	v_mfma_f32_16x16x128_f8f6f4 v[50:53], v[2:9], v[166:173], v[50:53]
	v_mfma_f32_16x16x128_f8f6f4 v[42:45], v[10:17], v[166:173], v[218:221]
	s_waitcnt lgkmcnt(2)
	v_mfma_f32_16x16x128_f8f6f4 v[34:37], v[2:9], v[174:181], v[222:225]
	v_mfma_f32_16x16x128_f8f6f4 v[26:29], v[10:17], v[174:181], v[226:229]
	s_waitcnt lgkmcnt(0)
	v_mfma_f32_16x16x128_f8f6f4 v[230:233], v[2:9], v[182:189], v[230:233]
	v_mfma_f32_16x16x128_f8f6f4 v[10:13], v[10:17], v[182:189], v[234:237]
	s_setprio 0
	s_barrier
	s_mov_b32 m0, s36
	s_add_i32 s33, s85, 0x2080
	buffer_load_dwordx4 v134, s[8:11], s33 offen lds
	s_add_i32 s85, s85, 0x22080
	s_mov_b32 m0, s37
	s_nop 0
	buffer_load_dwordx4 v134, s[8:11], s85 offen lds
	s_waitcnt vmcnt(6)
	s_barrier
	s_setprio 1
	v_mfma_f32_16x16x128_f8f6f4 v[54:57], v[142:149], v[158:165], v[54:57]
	v_mfma_f32_16x16x128_f8f6f4 v[46:49], v[150:157], v[158:165], v[238:241]
	v_mfma_f32_16x16x128_f8f6f4 v[38:41], v[142:149], v[166:173], v[242:245]
	v_mfma_f32_16x16x128_f8f6f4 v[30:33], v[150:157], v[166:173], v[246:249]
	v_mfma_f32_16x16x128_f8f6f4 v[22:25], v[142:149], v[174:181], v[250:253]
	v_mfma_f32_16x16x128_f8f6f4 v[14:17], v[150:157], v[174:181], v[130:133]
	v_mfma_f32_16x16x128_f8f6f4 v[6:9], v[142:149], v[182:189], v[66:69]
	v_mfma_f32_16x16x128_f8f6f4 v[2:5], v[150:157], v[182:189], v[190:193]
	s_setprio 0
	s_add_i32 s84, s84, 2
	s_addk_i32 s7, 0x1000
	s_addk_i32 s79, 0x100
	s_cmp_gt_u32 s84, 5
	s_barrier
	.p2align 6

.Lfw_13_b_p:
	s_barrier
	s_setprio 1
	v_mfma_f32_16x16x32_bf16 v[50:53], v[192:195], v[160:163], 0
	v_mfma_f32_16x16x32_bf16 v[42:45], v[200:203], v[160:163], 0
	v_mfma_f32_16x16x32_bf16 v[34:37], v[192:195], v[168:171], 0
	v_mfma_f32_16x16x32_bf16 v[26:29], v[200:203], v[168:171], 0
	v_mfma_f32_16x16x32_bf16 v[18:21], v[192:195], v[176:179], 0
	v_mfma_f32_16x16x32_bf16 v[10:13], v[200:203], v[176:179], 0
	v_mfma_f32_16x16x32_bf16 v[6:9], v[192:195], v[184:187], 0
	v_mfma_f32_16x16x32_bf16 v[2:5], v[200:203], v[184:187], 0
	v_mfma_f32_16x16x32_bf16 v[50:53], v[196:199], v[164:167], v[50:53]
	v_mfma_f32_16x16x32_bf16 v[42:45], v[204:207], v[164:167], v[42:45]
	v_mfma_f32_16x16x32_bf16 v[34:37], v[196:199], v[172:175], v[34:37]
	v_mfma_f32_16x16x32_bf16 v[26:29], v[204:207], v[172:175], v[26:29]
	v_mfma_f32_16x16x32_bf16 v[18:21], v[196:199], v[180:183], v[18:21]
	v_mfma_f32_16x16x32_bf16 v[10:13], v[204:207], v[180:183], v[10:13]
	v_mfma_f32_16x16x32_bf16 v[6:9], v[196:199], v[188:191], v[6:9]
	v_mfma_f32_16x16x32_bf16 v[2:5], v[204:207], v[188:191], v[2:5]
	s_setprio 0
	s_barrier
	ds_read_b128 v[136:139], v150
	ds_read_b128 v[140:143], v150 offset:1024
	ds_read_b128 v[152:155], v150 offset:2048
	ds_read_b128 v[156:159], v150 offset:3072
	s_mov_b32 m0, s28
	s_add_i32 s33, s86, 0x40000
	ds_read_b128 v[160:163], v148 offset:32768
	ds_read_b128 v[164:167], v148 offset:33792
	ds_read_b128 v[168:171], v148 offset:34816
	ds_read_b128 v[172:175], v148 offset:35840
	ds_read_b128 v[176:179], v148 offset:36864
	ds_read_b128 v[180:183], v148 offset:37888
	ds_read_b128 v[184:187], v148 offset:38912
	ds_read_b128 v[188:191], v148 offset:39936
	buffer_load_dwordx4 v1, s[40:43], s33 offen lds
	s_add_i32 s33, s86, 0x60000
	s_mov_b32 m0, s29
	s_nop 0
	buffer_load_dwordx4 v1, s[40:43], s33 offen lds
	s_waitcnt lgkmcnt(8)
	s_barrier
	s_waitcnt lgkmcnt(0)
	s_setprio 1
	s_waitcnt lgkmcnt(7)
	v_mfma_f32_16x16x32_bf16 v[126:129], v[136:139], v[160:163], v[126:129]
	v_mfma_f32_16x16x32_bf16 v[122:125], v[152:155], v[160:163], v[122:125]
	s_waitcnt lgkmcnt(5)
	v_mfma_f32_16x16x32_bf16 v[118:121], v[136:139], v[168:171], v[118:121]
	v_mfma_f32_16x16x32_bf16 v[110:113], v[152:155], v[168:171], v[110:113]
	s_waitcnt lgkmcnt(3)
	v_mfma_f32_16x16x32_bf16 v[102:105], v[136:139], v[176:179], v[102:105]
	v_mfma_f32_16x16x32_bf16 v[94:97], v[152:155], v[176:179], v[94:97]
	s_waitcnt lgkmcnt(1)
	v_mfma_f32_16x16x32_bf16 v[86:89], v[136:139], v[184:187], v[86:89]
	v_mfma_f32_16x16x32_bf16 v[78:81], v[152:155], v[184:187], v[78:81]
	v_mfma_f32_16x16x32_bf16 v[126:129], v[140:143], v[164:167], v[126:129]
	v_mfma_f32_16x16x32_bf16 v[122:125], v[156:159], v[164:167], v[122:125]
	v_mfma_f32_16x16x32_bf16 v[118:121], v[140:143], v[172:175], v[118:121]
	v_mfma_f32_16x16x32_bf16 v[110:113], v[156:159], v[172:175], v[110:113]
	v_mfma_f32_16x16x32_bf16 v[102:105], v[140:143], v[180:183], v[102:105]
	v_mfma_f32_16x16x32_bf16 v[94:97], v[156:159], v[180:183], v[94:97]
	s_waitcnt lgkmcnt(0)
	v_mfma_f32_16x16x32_bf16 v[86:89], v[140:143], v[188:191], v[86:89]
	v_mfma_f32_16x16x32_bf16 v[78:81], v[156:159], v[188:191], v[78:81]
	s_setprio 0
	s_barrier
	s_mov_b32 m0, s31
	s_or_b32 s33, s85, 0x80
	ds_read_b128 v[192:195], v151
	ds_read_b128 v[196:199], v151 offset:1024
	ds_read_b128 v[200:203], v151 offset:2048
	ds_read_b128 v[204:207], v151 offset:3072
	buffer_load_dwordx4 v144, s[8:11], s33 offen lds
	s_add_i32 s33, s85, 0x20080
	s_mov_b32 m0, s34
	s_nop 0
	buffer_load_dwordx4 v144, s[8:11], s33 offen lds
	s_waitcnt vmcnt(10)
	s_barrier
	s_waitcnt lgkmcnt(0)
	s_setprio 1
	s_waitcnt lgkmcnt(3)
	v_mfma_f32_16x16x32_bf16 v[114:117], v[192:195], v[160:163], v[114:117]
	s_waitcnt lgkmcnt(1)
	v_mfma_f32_16x16x32_bf16 v[106:109], v[200:203], v[160:163], v[106:109]
	v_mfma_f32_16x16x32_bf16 v[98:101], v[192:195], v[168:171], v[98:101]
	v_mfma_f32_16x16x32_bf16 v[90:93], v[200:203], v[168:171], v[90:93]
	v_mfma_f32_16x16x32_bf16 v[82:85], v[192:195], v[176:179], v[82:85]
	v_mfma_f32_16x16x32_bf16 v[74:77], v[200:203], v[176:179], v[74:77]
	v_mfma_f32_16x16x32_bf16 v[70:73], v[192:195], v[184:187], v[70:73]
	v_mfma_f32_16x16x32_bf16 v[66:69], v[200:203], v[184:187], v[66:69]
	v_mfma_f32_16x16x32_bf16 v[114:117], v[196:199], v[164:167], v[114:117]
	s_waitcnt lgkmcnt(0)
	v_mfma_f32_16x16x32_bf16 v[106:109], v[204:207], v[164:167], v[106:109]
	v_mfma_f32_16x16x32_bf16 v[98:101], v[196:199], v[172:175], v[98:101]
	v_mfma_f32_16x16x32_bf16 v[90:93], v[204:207], v[172:175], v[90:93]
	v_mfma_f32_16x16x32_bf16 v[82:85], v[196:199], v[180:183], v[82:85]
	v_mfma_f32_16x16x32_bf16 v[74:77], v[204:207], v[180:183], v[74:77]
	v_mfma_f32_16x16x32_bf16 v[70:73], v[196:199], v[188:191], v[70:73]
	v_mfma_f32_16x16x32_bf16 v[66:69], v[204:207], v[188:191], v[66:69]
	s_setprio 0
	s_mov_b32 m0, s35
	s_barrier
	ds_read_b128 v[160:163], v148 offset:49152
	ds_read_b128 v[164:167], v148 offset:50176
	ds_read_b128 v[168:171], v148 offset:51200
	ds_read_b128 v[172:175], v148 offset:52224
	ds_read_b128 v[176:179], v148 offset:53248
	ds_read_b128 v[180:183], v148 offset:54272
	ds_read_b128 v[184:187], v148 offset:55296
	ds_read_b128 v[188:191], v148 offset:56320
	buffer_load_dwordx4 v1, s[40:43], s87 offen lds
	s_add_i32 s86, s86, 0x20080
	s_mov_b32 m0, s36
	s_nop 0
	buffer_load_dwordx4 v1, s[40:43], s86 offen lds
	s_barrier
	s_waitcnt lgkmcnt(0)
	s_setprio 1
	s_waitcnt lgkmcnt(7)
	v_mfma_f32_16x16x32_bf16 v[62:65], v[136:139], v[160:163], v[62:65]
	v_mfma_f32_16x16x32_bf16 v[58:61], v[152:155], v[160:163], v[58:61]
	s_waitcnt lgkmcnt(5)
	v_mfma_f32_16x16x32_bf16 v[54:57], v[136:139], v[168:171], v[54:57]
	v_mfma_f32_16x16x32_bf16 v[46:49], v[152:155], v[168:171], v[46:49]
	s_waitcnt lgkmcnt(3)
	v_mfma_f32_16x16x32_bf16 v[38:41], v[136:139], v[176:179], v[38:41]
	v_mfma_f32_16x16x32_bf16 v[30:33], v[152:155], v[176:179], v[30:33]
	s_waitcnt lgkmcnt(1)
	v_mfma_f32_16x16x32_bf16 v[22:25], v[136:139], v[184:187], v[22:25]
	v_mfma_f32_16x16x32_bf16 v[14:17], v[152:155], v[184:187], v[14:17]
	v_mfma_f32_16x16x32_bf16 v[62:65], v[140:143], v[164:167], v[62:65]
	v_mfma_f32_16x16x32_bf16 v[58:61], v[156:159], v[164:167], v[58:61]
	v_mfma_f32_16x16x32_bf16 v[54:57], v[140:143], v[172:175], v[54:57]
	v_mfma_f32_16x16x32_bf16 v[46:49], v[156:159], v[172:175], v[46:49]
	v_mfma_f32_16x16x32_bf16 v[38:41], v[140:143], v[180:183], v[38:41]
	v_mfma_f32_16x16x32_bf16 v[30:33], v[156:159], v[180:183], v[30:33]
	s_waitcnt lgkmcnt(0)
	v_mfma_f32_16x16x32_bf16 v[22:25], v[140:143], v[188:191], v[22:25]
	v_mfma_f32_16x16x32_bf16 v[14:17], v[156:159], v[188:191], v[14:17]
	s_setprio 0
	s_barrier
	s_mov_b32 m0, s37
	s_add_i32 s33, s85, 0x40080
	buffer_load_dwordx4 v144, s[8:11], s33 offen lds
	s_add_i32 s85, s85, 0x60080
	s_mov_b32 m0, s38
	s_nop 0
	buffer_load_dwordx4 v144, s[8:11], s85 offen lds
	s_waitcnt vmcnt(6)
	s_barrier
	s_setprio 1
	v_mfma_f32_16x16x32_bf16 v[50:53], v[192:195], v[160:163], v[50:53]
	v_mfma_f32_16x16x32_bf16 v[42:45], v[200:203], v[160:163], v[42:45]
	v_mfma_f32_16x16x32_bf16 v[34:37], v[192:195], v[168:171], v[34:37]
	v_mfma_f32_16x16x32_bf16 v[26:29], v[200:203], v[168:171], v[26:29]
	v_mfma_f32_16x16x32_bf16 v[18:21], v[192:195], v[176:179], v[18:21]
	v_mfma_f32_16x16x32_bf16 v[10:13], v[200:203], v[176:179], v[10:13]
	v_mfma_f32_16x16x32_bf16 v[6:9], v[192:195], v[184:187], v[6:9]
	v_mfma_f32_16x16x32_bf16 v[2:5], v[200:203], v[184:187], v[2:5]
	v_mfma_f32_16x16x32_bf16 v[50:53], v[196:199], v[164:167], v[50:53]
	v_mfma_f32_16x16x32_bf16 v[42:45], v[204:207], v[164:167], v[42:45]
	v_mfma_f32_16x16x32_bf16 v[34:37], v[196:199], v[172:175], v[34:37]
	v_mfma_f32_16x16x32_bf16 v[26:29], v[204:207], v[172:175], v[26:29]
	v_mfma_f32_16x16x32_bf16 v[18:21], v[196:199], v[180:183], v[18:21]
	v_mfma_f32_16x16x32_bf16 v[10:13], v[204:207], v[180:183], v[10:13]
	v_mfma_f32_16x16x32_bf16 v[6:9], v[196:199], v[188:191], v[6:9]
	v_mfma_f32_16x16x32_bf16 v[2:5], v[204:207], v[188:191], v[2:5]
	s_setprio 0
	s_add_i32 s84, s84, 2
	s_addk_i32 s7, 0x100
	s_addk_i32 s79, 0x100
	s_cmp_gt_u32 s84, 13
	s_barrier
	.p2align 6

.Lfw_14_b_p:
	s_barrier
	s_setprio 1
	v_mfma_f32_16x16x32_bf16 v[54:57], v[178:181], v[146:149], 0
	v_mfma_f32_16x16x32_bf16 v[50:53], v[202:205], v[146:149], 0
	v_mfma_f32_16x16x32_bf16 v[38:41], v[178:181], v[154:157], 0
	v_mfma_f32_16x16x32_bf16 v[34:37], v[202:205], v[154:157], 0
	v_mfma_f32_16x16x32_bf16 v[22:25], v[178:181], v[162:165], 0
	v_mfma_f32_16x16x32_bf16 v[18:21], v[202:205], v[162:165], 0
	v_mfma_f32_16x16x32_bf16 v[6:9], v[178:181], v[170:173], 0
	v_mfma_f32_16x16x32_bf16 v[2:5], v[202:205], v[170:173], 0
	v_mfma_f32_16x16x32_bf16 v[54:57], v[182:185], v[150:153], v[54:57]
	v_mfma_f32_16x16x32_bf16 v[50:53], v[206:209], v[150:153], v[50:53]
	v_mfma_f32_16x16x32_bf16 v[38:41], v[182:185], v[158:161], v[38:41]
	v_mfma_f32_16x16x32_bf16 v[34:37], v[206:209], v[158:161], v[34:37]
	v_mfma_f32_16x16x32_bf16 v[22:25], v[182:185], v[166:169], v[22:25]
	v_mfma_f32_16x16x32_bf16 v[18:21], v[206:209], v[166:169], v[18:21]
	v_mfma_f32_16x16x32_bf16 v[6:9], v[182:185], v[174:177], v[6:9]
	v_mfma_f32_16x16x32_bf16 v[2:5], v[206:209], v[174:177], v[2:5]
	s_setprio 0
	s_barrier
	ds_read_b128 v[130:133], v199
	ds_read_b128 v[134:137], v199 offset:1024
	ds_read_b128 v[138:141], v199 offset:2048
	ds_read_b128 v[142:145], v199 offset:3072
	s_mov_b32 m0, s21
	s_add_i32 s33, s78, 0x40000
	ds_read_b128 v[146:149], v197 offset:32768
	ds_read_b128 v[150:153], v197 offset:33792
	ds_read_b128 v[154:157], v197 offset:34816
	ds_read_b128 v[158:161], v197 offset:35840
	ds_read_b128 v[162:165], v197 offset:36864
	ds_read_b128 v[166:169], v197 offset:37888
	ds_read_b128 v[170:173], v197 offset:38912
	ds_read_b128 v[174:177], v197 offset:39936
	buffer_load_dwordx4 v192, s[48:51], s33 offen lds
	s_add_i32 s33, s78, 0x60000
	s_mov_b32 m0, s22
	s_nop 0
	buffer_load_dwordx4 v192, s[48:51], s33 offen lds
	s_waitcnt lgkmcnt(8)
	s_barrier
	s_waitcnt lgkmcnt(0)
	s_setprio 1
	s_waitcnt lgkmcnt(7)
	v_mfma_f32_16x16x32_bf16 v[126:129], v[130:133], v[146:149], v[126:129]
	v_mfma_f32_16x16x32_bf16 v[122:125], v[138:141], v[146:149], v[122:125]
	s_waitcnt lgkmcnt(5)
	v_mfma_f32_16x16x32_bf16 v[110:113], v[130:133], v[154:157], v[110:113]
	v_mfma_f32_16x16x32_bf16 v[106:109], v[138:141], v[154:157], v[106:109]
	s_waitcnt lgkmcnt(3)
	v_mfma_f32_16x16x32_bf16 v[94:97], v[130:133], v[162:165], v[94:97]
	v_mfma_f32_16x16x32_bf16 v[90:93], v[138:141], v[162:165], v[90:93]
	s_waitcnt lgkmcnt(1)
	v_mfma_f32_16x16x32_bf16 v[78:81], v[130:133], v[170:173], v[78:81]
	v_mfma_f32_16x16x32_bf16 v[74:77], v[138:141], v[170:173], v[74:77]
	v_mfma_f32_16x16x32_bf16 v[126:129], v[134:137], v[150:153], v[126:129]
	v_mfma_f32_16x16x32_bf16 v[122:125], v[142:145], v[150:153], v[122:125]
	v_mfma_f32_16x16x32_bf16 v[110:113], v[134:137], v[158:161], v[110:113]
	v_mfma_f32_16x16x32_bf16 v[106:109], v[142:145], v[158:161], v[106:109]
	v_mfma_f32_16x16x32_bf16 v[94:97], v[134:137], v[166:169], v[94:97]
	v_mfma_f32_16x16x32_bf16 v[90:93], v[142:145], v[166:169], v[90:93]
	s_waitcnt lgkmcnt(0)
	v_mfma_f32_16x16x32_bf16 v[78:81], v[134:137], v[174:177], v[78:81]
	v_mfma_f32_16x16x32_bf16 v[74:77], v[142:145], v[174:177], v[74:77]
	s_setprio 0
	s_barrier
	s_mov_b32 m0, s28
	s_add_i32 s33, s73, 0x80
	ds_read_b128 v[178:181], v200
	ds_read_b128 v[182:185], v200 offset:1024
	ds_read_b128 v[202:205], v200 offset:2048
	ds_read_b128 v[206:209], v200 offset:3072
	buffer_load_dwordx4 v193, s[8:11], s33 offen lds
	s_add_i32 s33, s73, 0x20080
	s_mov_b32 m0, s29
	s_nop 0
	buffer_load_dwordx4 v193, s[8:11], s33 offen lds
	s_waitcnt vmcnt(10)
	s_barrier
	s_waitcnt lgkmcnt(0)
	s_setprio 1
	s_waitcnt lgkmcnt(3)
	v_mfma_f32_16x16x32_bf16 v[118:121], v[178:181], v[146:149], v[118:121]
	s_waitcnt lgkmcnt(1)
	v_mfma_f32_16x16x32_bf16 v[114:117], v[202:205], v[146:149], v[114:117]
	v_mfma_f32_16x16x32_bf16 v[102:105], v[178:181], v[154:157], v[102:105]
	v_mfma_f32_16x16x32_bf16 v[98:101], v[202:205], v[154:157], v[98:101]
	v_mfma_f32_16x16x32_bf16 v[86:89], v[178:181], v[162:165], v[86:89]
	v_mfma_f32_16x16x32_bf16 v[82:85], v[202:205], v[162:165], v[82:85]
	v_mfma_f32_16x16x32_bf16 v[70:73], v[178:181], v[170:173], v[70:73]
	v_mfma_f32_16x16x32_bf16 v[66:69], v[202:205], v[170:173], v[66:69]
	v_mfma_f32_16x16x32_bf16 v[118:121], v[182:185], v[150:153], v[118:121]
	s_waitcnt lgkmcnt(0)
	v_mfma_f32_16x16x32_bf16 v[114:117], v[206:209], v[150:153], v[114:117]
	v_mfma_f32_16x16x32_bf16 v[102:105], v[182:185], v[158:161], v[102:105]
	v_mfma_f32_16x16x32_bf16 v[98:101], v[206:209], v[158:161], v[98:101]
	v_mfma_f32_16x16x32_bf16 v[86:89], v[182:185], v[166:169], v[86:89]
	v_mfma_f32_16x16x32_bf16 v[82:85], v[206:209], v[166:169], v[82:85]
	v_mfma_f32_16x16x32_bf16 v[70:73], v[182:185], v[174:177], v[70:73]
	v_mfma_f32_16x16x32_bf16 v[66:69], v[206:209], v[174:177], v[66:69]
	s_setprio 0
	s_mov_b32 m0, s30
	s_barrier
	ds_read_b128 v[146:149], v197 offset:49152
	ds_read_b128 v[150:153], v197 offset:50176
	ds_read_b128 v[154:157], v197 offset:51200
	ds_read_b128 v[158:161], v197 offset:52224
	ds_read_b128 v[162:165], v197 offset:53248
	ds_read_b128 v[166:169], v197 offset:54272
	ds_read_b128 v[170:173], v197 offset:55296
	ds_read_b128 v[174:177], v197 offset:56320
	buffer_load_dwordx4 v192, s[48:51], s79 offen lds
	s_add_i32 s78, s78, 0x20080
	s_mov_b32 m0, s31
	s_nop 0
	buffer_load_dwordx4 v192, s[48:51], s78 offen lds
	s_barrier
	s_waitcnt lgkmcnt(0)
	s_setprio 1
	s_waitcnt lgkmcnt(7)
	v_mfma_f32_16x16x32_bf16 v[62:65], v[130:133], v[146:149], v[62:65]
	v_mfma_f32_16x16x32_bf16 v[58:61], v[138:141], v[146:149], v[58:61]
	s_waitcnt lgkmcnt(5)
	v_mfma_f32_16x16x32_bf16 v[46:49], v[130:133], v[154:157], v[46:49]
	v_mfma_f32_16x16x32_bf16 v[42:45], v[138:141], v[154:157], v[42:45]
	s_waitcnt lgkmcnt(3)
	v_mfma_f32_16x16x32_bf16 v[30:33], v[130:133], v[162:165], v[30:33]
	v_mfma_f32_16x16x32_bf16 v[26:29], v[138:141], v[162:165], v[26:29]
	s_waitcnt lgkmcnt(1)
	v_mfma_f32_16x16x32_bf16 v[14:17], v[130:133], v[170:173], v[14:17]
	v_mfma_f32_16x16x32_bf16 v[10:13], v[138:141], v[170:173], v[10:13]
	v_mfma_f32_16x16x32_bf16 v[62:65], v[134:137], v[150:153], v[62:65]
	v_mfma_f32_16x16x32_bf16 v[58:61], v[142:145], v[150:153], v[58:61]
	v_mfma_f32_16x16x32_bf16 v[46:49], v[134:137], v[158:161], v[46:49]
	v_mfma_f32_16x16x32_bf16 v[42:45], v[142:145], v[158:161], v[42:45]
	v_mfma_f32_16x16x32_bf16 v[30:33], v[134:137], v[166:169], v[30:33]
	v_mfma_f32_16x16x32_bf16 v[26:29], v[142:145], v[166:169], v[26:29]
	s_waitcnt lgkmcnt(0)
	v_mfma_f32_16x16x32_bf16 v[14:17], v[134:137], v[174:177], v[14:17]
	v_mfma_f32_16x16x32_bf16 v[10:13], v[142:145], v[174:177], v[10:13]
	s_setprio 0
	s_barrier
	s_mov_b32 m0, s34
	s_add_i32 s33, s73, 0x40080
	buffer_load_dwordx4 v193, s[8:11], s33 offen lds
	s_add_i32 s73, s73, 0x60080
	s_mov_b32 m0, s35
	s_nop 0
	buffer_load_dwordx4 v193, s[8:11], s73 offen lds
	s_waitcnt vmcnt(6)
	s_barrier
	s_setprio 1
	v_mfma_f32_16x16x32_bf16 v[54:57], v[178:181], v[146:149], v[54:57]
	v_mfma_f32_16x16x32_bf16 v[50:53], v[202:205], v[146:149], v[50:53]
	v_mfma_f32_16x16x32_bf16 v[38:41], v[178:181], v[154:157], v[38:41]
	v_mfma_f32_16x16x32_bf16 v[34:37], v[202:205], v[154:157], v[34:37]
	v_mfma_f32_16x16x32_bf16 v[22:25], v[178:181], v[162:165], v[22:25]
	v_mfma_f32_16x16x32_bf16 v[18:21], v[202:205], v[162:165], v[18:21]
	v_mfma_f32_16x16x32_bf16 v[6:9], v[178:181], v[170:173], v[6:9]
	v_mfma_f32_16x16x32_bf16 v[2:5], v[202:205], v[170:173], v[2:5]
	v_mfma_f32_16x16x32_bf16 v[54:57], v[182:185], v[150:153], v[54:57]
	v_mfma_f32_16x16x32_bf16 v[50:53], v[206:209], v[150:153], v[50:53]
	v_mfma_f32_16x16x32_bf16 v[38:41], v[182:185], v[158:161], v[38:41]
	v_mfma_f32_16x16x32_bf16 v[34:37], v[206:209], v[158:161], v[34:37]
	v_mfma_f32_16x16x32_bf16 v[22:25], v[182:185], v[166:169], v[22:25]
	v_mfma_f32_16x16x32_bf16 v[18:21], v[206:209], v[166:169], v[18:21]
	v_mfma_f32_16x16x32_bf16 v[6:9], v[182:185], v[174:177], v[6:9]
	v_mfma_f32_16x16x32_bf16 v[2:5], v[206:209], v[174:177], v[2:5]
	s_setprio 0
	s_add_i32 s13, s13, 2
	s_addk_i32 s7, 0x100
	s_addk_i32 s12, 0x100
	s_cmp_gt_u32 s13, 13
	s_barrier
	.p2align 6

.LBB0_3110:
	v_bfe_u32 v2, v194, 16, 16
	v_lshl_add_u32 v195, v2, 10, v184
	v_bfe_u32 v2, v193, 16, 16
	v_mov_b32_e32 v50, 0
	v_lshl_add_u32 v196, v2, 10, v184
	s_mov_b32 s8, -2
	s_movk_i32 s9, 0x100
	s_branch .LBB0_3112_pr3
	.p2align 6

.Lfw_15_b:
	s_barrier
	s_setprio 1
	v_mfma_f32_16x16x128_f8f6f4 v[106:109], v[200:207], v[18:25], v[106:109]
	v_mfma_f32_16x16x128_f8f6f4 v[98:101], v[208:215], v[18:25], v[98:101]
	v_mfma_f32_16x16x128_f8f6f4 v[90:93], v[200:207], v[26:33], v[90:93]
	v_mfma_f32_16x16x128_f8f6f4 v[82:85], v[208:215], v[26:33], v[82:85]
	v_mfma_f32_16x16x128_f8f6f4 v[74:77], v[200:207], v[34:41], v[74:77]
	v_mfma_f32_16x16x128_f8f6f4 v[66:69], v[208:215], v[34:41], v[66:69]
	v_mfma_f32_16x16x128_f8f6f4 v[58:61], v[200:207], v[42:49], v[58:61]
	v_mfma_f32_16x16x128_f8f6f4 v[50:53], v[208:215], v[42:49], v[50:53]
	s_setprio 0
	v_add_u32_e32 v14, 0x18000, v190
	s_barrier
	ds_read_b128 v[2:5], v14
	ds_read_b128 v[6:9], v14 offset:1024
	ds_read_b128 v[10:13], v14 offset:2048
	ds_read_b128 v[14:17], v14 offset:3072
	s_mov_b32 m0, s22
	ds_read_b128 v[18:21], v192 offset:32768
	ds_read_b128 v[22:25], v192 offset:33792
	ds_read_b128 v[26:29], v192 offset:34816
	ds_read_b128 v[30:33], v192 offset:35840
	ds_read_b128 v[34:37], v192 offset:36864
	ds_read_b128 v[38:41], v192 offset:37888
	ds_read_b128 v[42:45], v192 offset:38912
	ds_read_b128 v[46:49], v192 offset:39936
	buffer_load_dwordx4 v197, s[40:43], s57 offen lds
	s_mov_b32 m0, s23
	s_nop 0
	buffer_load_dwordx4 v198, s[40:43], s57 offen lds
	s_waitcnt lgkmcnt(8)
	s_barrier
	s_waitcnt lgkmcnt(0)
	s_setprio 1
	s_waitcnt lgkmcnt(6)
	v_mfma_f32_16x16x128_f8f6f4 v[174:177], v[2:9], v[18:25], v[174:177]
	v_mfma_f32_16x16x128_f8f6f4 v[166:169], v[10:17], v[18:25], v[166:169]
	s_waitcnt lgkmcnt(4)
	v_mfma_f32_16x16x128_f8f6f4 v[158:161], v[2:9], v[26:33], v[158:161]
	v_mfma_f32_16x16x128_f8f6f4 v[150:153], v[10:17], v[26:33], v[150:153]
	s_waitcnt lgkmcnt(2)
	v_mfma_f32_16x16x128_f8f6f4 v[142:145], v[2:9], v[34:41], v[142:145]
	v_mfma_f32_16x16x128_f8f6f4 v[134:137], v[10:17], v[34:41], v[134:137]
	s_waitcnt lgkmcnt(0)
	v_mfma_f32_16x16x128_f8f6f4 v[126:129], v[2:9], v[42:49], v[126:129]
	v_mfma_f32_16x16x128_f8f6f4 v[118:121], v[10:17], v[42:49], v[118:121]
	s_setprio 0
	s_barrier
	s_mov_b32 m0, s25
	v_add_u32_e32 v197, 0x1c000, v190
	ds_read_b128 v[198:201], v197
	ds_read_b128 v[202:205], v197 offset:1024
	ds_read_b128 v[206:209], v197 offset:2048
	ds_read_b128 v[210:213], v197 offset:3072
	buffer_load_dwordx4 v185, s[12:15], s7 offen lds
	s_add_i32 s7, s6, 0x10080
	s_mov_b32 m0, s26
	s_nop 0
	buffer_load_dwordx4 v185, s[12:15], s7 offen lds
	s_waitcnt vmcnt(10)
	s_barrier
	s_waitcnt lgkmcnt(0)
	s_setprio 1
	s_waitcnt lgkmcnt(2)
	v_mfma_f32_16x16x128_f8f6f4 v[170:173], v[198:205], v[18:25], v[170:173]
	s_waitcnt lgkmcnt(0)
	v_mfma_f32_16x16x128_f8f6f4 v[162:165], v[206:213], v[18:25], v[162:165]
	v_mfma_f32_16x16x128_f8f6f4 v[154:157], v[198:205], v[26:33], v[154:157]
	v_mfma_f32_16x16x128_f8f6f4 v[146:149], v[206:213], v[26:33], v[146:149]
	v_mfma_f32_16x16x128_f8f6f4 v[138:141], v[198:205], v[34:41], v[138:141]
	v_mfma_f32_16x16x128_f8f6f4 v[130:133], v[206:213], v[34:41], v[130:133]
	v_mfma_f32_16x16x128_f8f6f4 v[122:125], v[198:205], v[42:49], v[122:125]
	v_mfma_f32_16x16x128_f8f6f4 v[114:117], v[206:213], v[42:49], v[114:117]
	s_setprio 0
	s_mov_b32 m0, s27
	s_barrier
	ds_read_b128 v[18:21], v192 offset:49152
	ds_read_b128 v[22:25], v192 offset:50176
	ds_read_b128 v[26:29], v192 offset:51200
	ds_read_b128 v[30:33], v192 offset:52224
	ds_read_b128 v[34:37], v192 offset:53248
	ds_read_b128 v[38:41], v192 offset:54272
	ds_read_b128 v[42:45], v192 offset:55296
	ds_read_b128 v[46:49], v192 offset:56320
	buffer_load_dwordx4 v216, s[40:43], s51 offen lds
	s_mov_b32 m0, s28
	s_nop 0
	buffer_load_dwordx4 v217, s[40:43], s51 offen lds
	s_barrier
	s_waitcnt lgkmcnt(0)
	s_setprio 1
	s_waitcnt lgkmcnt(6)
	v_mfma_f32_16x16x128_f8f6f4 v[110:113], v[2:9], v[18:25], v[110:113]
	v_mfma_f32_16x16x128_f8f6f4 v[102:105], v[10:17], v[18:25], v[102:105]
	s_waitcnt lgkmcnt(4)
	v_mfma_f32_16x16x128_f8f6f4 v[94:97], v[2:9], v[26:33], v[94:97]
	v_mfma_f32_16x16x128_f8f6f4 v[86:89], v[10:17], v[26:33], v[86:89]
	s_waitcnt lgkmcnt(2)
	v_mfma_f32_16x16x128_f8f6f4 v[78:81], v[2:9], v[34:41], v[78:81]
	v_mfma_f32_16x16x128_f8f6f4 v[70:73], v[10:17], v[34:41], v[70:73]
	s_waitcnt lgkmcnt(0)
	v_mfma_f32_16x16x128_f8f6f4 v[62:65], v[2:9], v[42:49], v[62:65]
	v_mfma_f32_16x16x128_f8f6f4 v[54:57], v[10:17], v[42:49], v[54:57]
	s_setprio 0
	s_barrier
	s_mov_b32 m0, s29
	s_add_i32 s7, s6, 0x20080
	buffer_load_dwordx4 v185, s[12:15], s7 offen lds
	s_add_i32 s6, s6, 0x30080
	s_mov_b32 m0, s30
	s_nop 0
	buffer_load_dwordx4 v185, s[12:15], s6 offen lds
	s_waitcnt vmcnt(6)
	s_barrier
	s_setprio 1
	v_mfma_f32_16x16x128_f8f6f4 v[106:109], v[198:205], v[18:25], v[106:109]
	v_mfma_f32_16x16x128_f8f6f4 v[98:101], v[206:213], v[18:25], v[98:101]
	v_mfma_f32_16x16x128_f8f6f4 v[90:93], v[198:205], v[26:33], v[90:93]
	v_mfma_f32_16x16x128_f8f6f4 v[82:85], v[206:213], v[26:33], v[82:85]
	v_mfma_f32_16x16x128_f8f6f4 v[74:77], v[198:205], v[34:41], v[74:77]
	v_mfma_f32_16x16x128_f8f6f4 v[66:69], v[206:213], v[34:41], v[66:69]
	v_mfma_f32_16x16x128_f8f6f4 v[58:61], v[198:205], v[42:49], v[58:61]
	v_mfma_f32_16x16x128_f8f6f4 v[50:53], v[206:213], v[42:49], v[50:53]
	s_setprio 0
	s_add_i32 s8, s8, 2
	s_addk_i32 s9, 0x100
	s_cmp_gt_u32 s8, 5
	s_barrier
	s_cbranch_scc1 .LBB0_3099
	.p2align 6

.Lfw_16_b_p:
	s_barrier
	s_setprio 1
	v_mfma_f32_16x16x128_f8f6f4 v[54:57], v[122:129], v[66:73], 0
	v_mfma_f32_16x16x128_f8f6f4 v[240:243], v[192:199], v[66:73], 0
	v_mfma_f32_16x16x128_f8f6f4 v[244:247], v[122:129], v[74:81], 0
	v_mfma_f32_16x16x128_f8f6f4 v[248:251], v[192:199], v[74:81], 0
	v_mfma_f32_16x16x128_f8f6f4 v[130:133], v[122:129], v[82:89], 0
	v_mfma_f32_16x16x128_f8f6f4 v[140:143], v[192:199], v[82:89], 0
	v_mfma_f32_16x16x128_f8f6f4 v[66:69], v[122:129], v[90:97], 0
	v_mfma_f32_16x16x128_f8f6f4 v[192:195], v[192:199], v[90:97], 0
	s_setprio 0
	s_barrier
	s_nop 4
	ds_read_b128 v[2:5], v252
	ds_read_b128 v[6:9], v252 offset:1024
	ds_read_b128 v[10:13], v252 offset:2048
	ds_read_b128 v[14:17], v252 offset:3072
	s_mov_b32 m0, s27
	s_add_i32 s33, s74, 0x20000
	ds_read_b128 v[18:21], v139 offset:32768
	ds_read_b128 v[22:25], v139 offset:33792
	ds_read_b128 v[26:29], v139 offset:34816
	ds_read_b128 v[30:33], v139 offset:35840
	ds_read_b128 v[34:37], v139 offset:36864
	ds_read_b128 v[38:41], v139 offset:37888
	ds_read_b128 v[42:45], v139 offset:38912
	ds_read_b128 v[46:49], v139 offset:39936
	buffer_load_dwordx4 v134, s[44:47], s33 offen lds
	s_add_i32 s33, s74, 0x30000
	s_mov_b32 m0, s28
	s_nop 0
	buffer_load_dwordx4 v134, s[44:47], s33 offen lds
	s_waitcnt lgkmcnt(8)
	s_barrier
	s_waitcnt lgkmcnt(0)
	s_setprio 1
	s_waitcnt lgkmcnt(6)
	v_mfma_f32_16x16x128_f8f6f4 v[126:129], v[2:9], v[18:25], v[200:203]
	v_mfma_f32_16x16x128_f8f6f4 v[122:125], v[10:17], v[18:25], v[204:207]
	s_waitcnt lgkmcnt(4)
	v_mfma_f32_16x16x128_f8f6f4 v[114:117], v[2:9], v[26:33], v[114:117]
	v_mfma_f32_16x16x128_f8f6f4 v[106:109], v[10:17], v[26:33], v[106:109]
	s_waitcnt lgkmcnt(2)
	v_mfma_f32_16x16x128_f8f6f4 v[98:101], v[2:9], v[34:41], v[98:101]
	v_mfma_f32_16x16x128_f8f6f4 v[90:93], v[10:17], v[34:41], v[208:211]
	s_waitcnt lgkmcnt(0)
	v_mfma_f32_16x16x128_f8f6f4 v[82:85], v[2:9], v[42:49], v[212:215]
	v_mfma_f32_16x16x128_f8f6f4 v[74:77], v[10:17], v[42:49], v[216:219]
	s_setprio 0
	s_barrier
	s_mov_b32 m0, s30
	s_add_i32 s33, s73, 0x80
	ds_read_b128 v[144:147], v253
	ds_read_b128 v[148:151], v253 offset:1024
	ds_read_b128 v[152:155], v253 offset:2048
	ds_read_b128 v[156:159], v253 offset:3072
	buffer_load_dwordx4 v135, s[8:11], s33 offen lds
	s_add_i32 s33, s73, 0x20080
	s_mov_b32 m0, s31
	s_nop 0
	buffer_load_dwordx4 v135, s[8:11], s33 offen lds
	s_waitcnt vmcnt(10)
	s_barrier
	s_waitcnt lgkmcnt(0)
	s_setprio 1
	s_waitcnt lgkmcnt(2)
	v_mfma_f32_16x16x128_f8f6f4 v[118:121], v[144:151], v[18:25], v[118:121]
	s_waitcnt lgkmcnt(0)
	v_mfma_f32_16x16x128_f8f6f4 v[110:113], v[152:159], v[18:25], v[110:113]
	v_mfma_f32_16x16x128_f8f6f4 v[102:105], v[144:151], v[26:33], v[102:105]
	v_mfma_f32_16x16x128_f8f6f4 v[94:97], v[152:159], v[26:33], v[160:163]
	v_mfma_f32_16x16x128_f8f6f4 v[86:89], v[144:151], v[34:41], v[164:167]
	v_mfma_f32_16x16x128_f8f6f4 v[78:81], v[152:159], v[34:41], v[168:171]
	v_mfma_f32_16x16x128_f8f6f4 v[70:73], v[144:151], v[42:49], v[172:175]
	v_mfma_f32_16x16x128_f8f6f4 v[18:21], v[152:159], v[42:49], v[176:179]
	s_setprio 0
	s_mov_b32 m0, s34
	s_barrier
	ds_read_b128 v[160:163], v139 offset:49152
	ds_read_b128 v[164:167], v139 offset:50176
	ds_read_b128 v[168:171], v139 offset:51200
	ds_read_b128 v[172:175], v139 offset:52224
	ds_read_b128 v[176:179], v139 offset:53248
	ds_read_b128 v[180:183], v139 offset:54272
	ds_read_b128 v[184:187], v139 offset:55296
	ds_read_b128 v[188:191], v139 offset:56320
	buffer_load_dwordx4 v134, s[44:47], s75 offen lds
	s_add_i32 s74, s74, 0x10800
	s_mov_b32 m0, s35
	s_nop 0
	buffer_load_dwordx4 v134, s[44:47], s74 offen lds
	s_barrier
	s_waitcnt lgkmcnt(0)
	s_setprio 1
	s_waitcnt lgkmcnt(6)
	v_mfma_f32_16x16x128_f8f6f4 v[62:65], v[2:9], v[160:167], v[62:65]
	v_mfma_f32_16x16x128_f8f6f4 v[58:61], v[10:17], v[160:167], v[58:61]
	s_waitcnt lgkmcnt(4)
	v_mfma_f32_16x16x128_f8f6f4 v[50:53], v[2:9], v[168:175], v[50:53]
	v_mfma_f32_16x16x128_f8f6f4 v[42:45], v[10:17], v[168:175], v[220:223]
	s_waitcnt lgkmcnt(2)
	v_mfma_f32_16x16x128_f8f6f4 v[34:37], v[2:9], v[176:183], v[224:227]
	v_mfma_f32_16x16x128_f8f6f4 v[26:29], v[10:17], v[176:183], v[228:231]
	s_waitcnt lgkmcnt(0)
	v_mfma_f32_16x16x128_f8f6f4 v[232:235], v[2:9], v[184:191], v[232:235]
	v_mfma_f32_16x16x128_f8f6f4 v[10:13], v[10:17], v[184:191], v[236:239]
	s_setprio 0
	s_barrier
	s_mov_b32 m0, s36
	s_add_i32 s33, s73, 0x2080
	buffer_load_dwordx4 v135, s[8:11], s33 offen lds
	s_add_i32 s73, s73, 0x22080
	s_mov_b32 m0, s37
	s_nop 0
	buffer_load_dwordx4 v135, s[8:11], s73 offen lds
	s_waitcnt vmcnt(6)
	s_barrier
	s_setprio 1
	v_mfma_f32_16x16x128_f8f6f4 v[54:57], v[144:151], v[160:167], v[54:57]
	v_mfma_f32_16x16x128_f8f6f4 v[46:49], v[152:159], v[160:167], v[240:243]
	v_mfma_f32_16x16x128_f8f6f4 v[38:41], v[144:151], v[168:175], v[244:247]
	v_mfma_f32_16x16x128_f8f6f4 v[30:33], v[152:159], v[168:175], v[248:251]
	v_mfma_f32_16x16x128_f8f6f4 v[22:25], v[144:151], v[176:183], v[130:133]
	v_mfma_f32_16x16x128_f8f6f4 v[14:17], v[152:159], v[176:183], v[140:143]
	v_mfma_f32_16x16x128_f8f6f4 v[6:9], v[144:151], v[184:191], v[66:69]
	v_mfma_f32_16x16x128_f8f6f4 v[2:5], v[152:159], v[184:191], v[192:195]
	s_setprio 0
	s_add_i32 s72, s72, 2
	s_addk_i32 s7, 0x1000
	s_addk_i32 s71, 0x100
	s_cmp_gt_u32 s72, 5
	s_barrier
	.p2align 6
